# K-loop: s_barrier moved before last 4 MFMAs of each MMA segment with s_setprio 2 (handoff overlap)
# baseline (speedup 1.0000x reference)
; #define PG8_STAGE(bufoff, gbase, voff) do { _Pragma("unroll") for (int _i = 0; _i < 2; ++_i) \
;         __builtin_amdgcn_global_load_lds((const unsigned*)((const char*)(gbase) + (voff)[_i]), (LAS unsigned*)(lds + (bufoff) + ldsw + _i * 8192), 16, 0, 0); } while (0)
; #define PG8_LDA(dst, b, h) do { _Pragma("unroll") for (int m = 0; m < 4; ++m) _Pragma("unroll") for (int k = 0; k < 2; ++k) dst[m][k] = *(const LAS bf16x8*)(lds + PG8_SA(b, h) + aoff + m * 2048 + k * 1024); } while (0)
; #define PG8_LDB(dst, b, h) do { _Pragma("unroll") for (int n = 0; n < 2; ++n) _Pragma("unroll") for (int k = 0; k < 2; ++k) dst[n][k] = *(const LAS bf16x8*)(lds + PG8_SB(b, h) + boff + n * 2048 + k * 1024); } while (0)
; #define PG8_MMA(ai, bj, At, Bt) do { __builtin_amdgcn_s_setprio(1); _Pragma("unroll") for (int m = 0; m < 4; ++m) _Pragma("unroll") for (int n = 0; n < 2; ++n) _Pragma("unroll") for (int k = 0; k < 2; ++k) \
;         acc[ai][bj][m][n] = __builtin_amdgcn_mfma_f32_16x16x32_bf16(Bt[n][k], At[m][k], acc[ai][bj][m][n], 0, 0, 0); __builtin_amdgcn_s_setprio(0); } while (0)
; #define PG8_WAIT_V(n) asm volatile("s_waitcnt vmcnt(" #n ")" ::: "memory")
; #define PG8_WAIT_L(n) asm volatile("s_waitcnt lgkmcnt(" #n ")" ::: "memory")
; #define PG8_BAR __builtin_amdgcn_s_barrier()
; #define PG8_SCHED __builtin_amdgcn_sched_barrier(0)
; template <class Epi>
; __device__ __forceinline__ void gemm_phase(LAS unsigned char* lds, const Sched& S, const Epi& E) {
;     ...
;             const bool last = (t == nt - 2);
;             const char* a1 = cA + (size_t)(t + 1) * kstep;
;             const char* a2 = last ? nA : cA + (size_t)(t + 2) * kstep; const char* b2 = last ? nB : cB + (size_t)(t + 2) * kstep;
;             const char* a3 = a2 + kstep; const char* b3 = b2 + kstep;
;             PG8_LDB(B0, 0, 0); PG8_LDB(B1, 0, 1); PG8_SCHED; PG8_LDA(At, 0, 0); PG8_STAGE(PG8_SA(1, 1), a1 + hstepA, voffA);
;             PG8_WAIT_V(8); PG8_WAIT_L(0); PG8_BAR; PG8_MMA(0, 0, At, B0); PG8_MMA(0, 1, At, B1); PG8_BAR; PG8_SCHED;
;             PG8_LDA(At, 0, 1); PG8_STAGE(PG8_SB(0, 0), b2, voffB); PG8_STAGE(PG8_SB(0, 1), b2 + hstepB, voffB); PG8_STAGE(PG8_SA(0, 0), a2, voffA);
.LBB0_735:
	s_add_u32 s24, s22, 0xfff80080
	s_addc_u32 s25, s23, -1
	s_add_i32 s49, 0, 0x10000
	s_cmp_eq_u32 s68, 28
	s_cselect_b32 s27, s19, s25
	s_cselect_b32 s26, s18, s24
	v_add_u32_e32 v153, s49, v149
	s_cselect_b32 s25, s21, s11
	s_cselect_b32 s24, s20, s9
	s_add_i32 s69, 0, 0x14000
	ds_read_b128 v[140:143], v153
	ds_read_b128 v[144:147], v153 offset:1024
	ds_read_b128 v[154:157], v153 offset:2048
	ds_read_b128 v[158:161], v153 offset:3072
	v_add_u32_e32 v153, s69, v149
	ds_read_b128 v[162:165], v153
	ds_read_b128 v[176:179], v153 offset:1024
	ds_read_b128 v[180:183], v153 offset:2048
	ds_read_b128 v[184:187], v153 offset:3072
	v_lshl_add_u64 v[166:167], s[22:23], 0, v[136:137]
	s_add_i32 m0, s17, 0xc000
	ds_read_b128 v[188:191], v152
	ds_read_b128 v[192:195], v152 offset:1024
	ds_read_b128 v[196:199], v152 offset:2048
	ds_read_b128 v[222:225], v152 offset:3072
	ds_read_b128 v[226:229], v152 offset:4096
	ds_read_b128 v[230:233], v152 offset:5120
	ds_read_b128 v[234:237], v152 offset:6144
	ds_read_b128 v[238:241], v152 offset:7168
	global_load_lds_dwordx4 v[166:167], off
	v_lshl_add_u64 v[166:167], s[22:23], 0, v[138:139]
	s_add_i32 m0, s17, 0xe000
	s_nop 0
	global_load_lds_dwordx4 v[166:167], off
	s_waitcnt vmcnt(8)
	s_waitcnt lgkmcnt(0)
	s_barrier
	s_setprio 1
	s_waitcnt lgkmcnt(0)
	v_mfma_f32_16x16x32_bf16 v[126:129], v[140:143], v[188:191], v[126:129]
	v_mfma_f32_16x16x32_bf16 v[122:125], v[154:157], v[188:191], v[122:125]
	v_mfma_f32_16x16x32_bf16 v[114:117], v[140:143], v[196:199], v[114:117]
	v_mfma_f32_16x16x32_bf16 v[106:109], v[154:157], v[196:199], v[106:109]
	v_mfma_f32_16x16x32_bf16 v[98:101], v[140:143], v[226:229], v[98:101]
	v_mfma_f32_16x16x32_bf16 v[90:93], v[154:157], v[226:229], v[90:93]
	v_mfma_f32_16x16x32_bf16 v[82:85], v[140:143], v[234:237], v[82:85]
	v_mfma_f32_16x16x32_bf16 v[74:77], v[154:157], v[234:237], v[74:77]
	v_mfma_f32_16x16x32_bf16 v[126:129], v[144:147], v[192:195], v[126:129]
	v_mfma_f32_16x16x32_bf16 v[122:125], v[158:161], v[192:195], v[122:125]
	v_mfma_f32_16x16x32_bf16 v[114:117], v[144:147], v[222:225], v[114:117]
	v_mfma_f32_16x16x32_bf16 v[106:109], v[158:161], v[222:225], v[106:109]
	v_mfma_f32_16x16x32_bf16 v[98:101], v[144:147], v[230:233], v[98:101]
	v_mfma_f32_16x16x32_bf16 v[90:93], v[158:161], v[230:233], v[90:93]
	v_mfma_f32_16x16x32_bf16 v[82:85], v[144:147], v[238:241], v[82:85]
	v_mfma_f32_16x16x32_bf16 v[74:77], v[158:161], v[238:241], v[74:77]
	s_setprio 0
	s_setprio 1
	v_mfma_f32_16x16x32_bf16 v[118:121], v[162:165], v[188:191], v[118:121]
	v_mfma_f32_16x16x32_bf16 v[110:113], v[180:183], v[188:191], v[110:113]
	v_mfma_f32_16x16x32_bf16 v[102:105], v[162:165], v[196:199], v[102:105]
	v_mfma_f32_16x16x32_bf16 v[94:97], v[180:183], v[196:199], v[94:97]
	v_mfma_f32_16x16x32_bf16 v[86:89], v[162:165], v[226:229], v[86:89]
	v_mfma_f32_16x16x32_bf16 v[78:81], v[180:183], v[226:229], v[78:81]
	v_mfma_f32_16x16x32_bf16 v[70:73], v[162:165], v[234:237], v[70:73]
	v_mfma_f32_16x16x32_bf16 v[66:69], v[180:183], v[234:237], v[66:69]
	v_mfma_f32_16x16x32_bf16 v[118:121], v[176:179], v[192:195], v[118:121]
	v_mfma_f32_16x16x32_bf16 v[110:113], v[184:187], v[192:195], v[110:113]
	v_mfma_f32_16x16x32_bf16 v[102:105], v[176:179], v[222:225], v[102:105]
	v_mfma_f32_16x16x32_bf16 v[94:97], v[184:187], v[222:225], v[94:97]
	s_setprio 2
	s_barrier
	v_mfma_f32_16x16x32_bf16 v[86:89], v[176:179], v[230:233], v[86:89]
	v_mfma_f32_16x16x32_bf16 v[78:81], v[184:187], v[230:233], v[78:81]
	v_mfma_f32_16x16x32_bf16 v[70:73], v[176:179], v[238:241], v[70:73]
	v_mfma_f32_16x16x32_bf16 v[66:69], v[184:187], v[238:241], v[66:69]
	s_setprio 0
	s_add_i32 s49, s49, s35
	v_lshl_add_u64 v[166:167], s[24:25], 0, v[168:169]
	s_mov_b32 m0, s49
	ds_read_b128 v[188:191], v152 offset:16384
	ds_read_b128 v[192:195], v152 offset:17408
	ds_read_b128 v[196:199], v152 offset:18432
	ds_read_b128 v[222:225], v152 offset:19456
	ds_read_b128 v[226:229], v152 offset:20480
	ds_read_b128 v[230:233], v152 offset:21504
	ds_read_b128 v[234:237], v152 offset:22528
	ds_read_b128 v[238:241], v152 offset:23552
	global_load_lds_dwordx4 v[166:167], off
	s_add_i32 m0, s49, 0x2000
	s_add_u32 s94, s24, 0x80000
	v_lshl_add_u64 v[200:201], s[24:25], 0, v[134:135]
	s_addc_u32 s95, s25, 0
	s_add_i32 s49, s69, s35
	global_load_lds_dwordx4 v[200:201], off
	v_lshl_add_u64 v[242:243], s[94:95], 0, v[168:169]
	s_mov_b32 m0, s49
	v_lshl_add_u64 v[244:245], s[26:27], 0, v[132:133]
	global_load_lds_dwordx4 v[242:243], off
	v_lshl_add_u64 v[242:243], s[94:95], 0, v[134:135]
	s_add_i32 m0, s49, 0x2000
	s_nop 0
	global_load_lds_dwordx4 v[242:243], off
	v_lshl_add_u64 v[242:243], s[26:27], 0, v[130:131]
	s_mov_b32 m0, s17
	s_nop 0
	global_load_lds_dwordx4 v[242:243], off
	s_mov_b32 m0, s36
	s_nop 0
	global_load_lds_dwordx4 v[244:245], off
	s_waitcnt vmcnt(8)
	s_waitcnt lgkmcnt(0)
	s_barrier
; #define PG8_STAGE(bufoff, gbase, voff) do { _Pragma("unroll") for (int _i = 0; _i < 2; ++_i) \
;         __builtin_amdgcn_global_load_lds((const unsigned*)((const char*)(gbase) + (voff)[_i]), (LAS unsigned*)(lds + (bufoff) + ldsw + _i * 8192), 16, 0, 0); } while (0)
; #define PG8_LDA(dst, b, h) do { _Pragma("unroll") for (int m = 0; m < 4; ++m) _Pragma("unroll") for (int k = 0; k < 2; ++k) dst[m][k] = *(const LAS bf16x8*)(lds + PG8_SA(b, h) + aoff + m * 2048 + k * 1024); } while (0)
; #define PG8_LDB(dst, b, h) do { _Pragma("unroll") for (int n = 0; n < 2; ++n) _Pragma("unroll") for (int k = 0; k < 2; ++k) dst[n][k] = *(const LAS bf16x8*)(lds + PG8_SB(b, h) + boff + n * 2048 + k * 1024); } while (0)
; #define PG8_MMA(ai, bj, At, Bt) do { __builtin_amdgcn_s_setprio(1); _Pragma("unroll") for (int m = 0; m < 4; ++m) _Pragma("unroll") for (int n = 0; n < 2; ++n) _Pragma("unroll") for (int k = 0; k < 2; ++k) \
;         acc[ai][bj][m][n] = __builtin_amdgcn_mfma_f32_16x16x32_bf16(Bt[n][k], At[m][k], acc[ai][bj][m][n], 0, 0, 0); __builtin_amdgcn_s_setprio(0); } while (0)
; #define PG8_WAIT_V(n) asm volatile("s_waitcnt vmcnt(" #n ")" ::: "memory")
; #define PG8_WAIT_L(n) asm volatile("s_waitcnt lgkmcnt(" #n ")" ::: "memory")
; #define PG8_BAR __builtin_amdgcn_s_barrier()
; #define PG8_SCHED __builtin_amdgcn_sched_barrier(0)
; template <class Epi>
; __device__ __forceinline__ void gemm_phase(LAS unsigned char* lds, const Sched& S, const Epi& E) {
;     ...
;             PG8_WAIT_V(8); PG8_WAIT_L(0); PG8_BAR; PG8_MMA(1, 0, At, B0); PG8_MMA(1, 1, At, B1); PG8_BAR; PG8_SCHED;
;             PG8_LDB(B0, 1, 0); PG8_LDB(B1, 1, 1); PG8_SCHED; PG8_LDA(At, 1, 0); PG8_STAGE(PG8_SA(0, 1), a2 + hstepA, voffA);
;             PG8_WAIT_V(8); PG8_WAIT_L(0); PG8_BAR; PG8_MMA(0, 0, At, B0); PG8_MMA(0, 1, At, B1); PG8_BAR; PG8_SCHED;
	s_setprio 1
	s_waitcnt lgkmcnt(0)
	v_mfma_f32_16x16x32_bf16 v[62:65], v[140:143], v[188:191], v[62:65]
	v_mfma_f32_16x16x32_bf16 v[58:61], v[154:157], v[188:191], v[58:61]
	v_mfma_f32_16x16x32_bf16 v[50:53], v[140:143], v[196:199], v[50:53]
	v_mfma_f32_16x16x32_bf16 v[42:45], v[154:157], v[196:199], v[42:45]
	v_mfma_f32_16x16x32_bf16 v[34:37], v[140:143], v[226:229], v[34:37]
	v_mfma_f32_16x16x32_bf16 v[26:29], v[154:157], v[226:229], v[26:29]
	v_mfma_f32_16x16x32_bf16 v[18:21], v[140:143], v[234:237], v[18:21]
	v_mfma_f32_16x16x32_bf16 v[10:13], v[154:157], v[234:237], v[10:13]
	v_mfma_f32_16x16x32_bf16 v[62:65], v[144:147], v[192:195], v[62:65]
	v_mfma_f32_16x16x32_bf16 v[58:61], v[158:161], v[192:195], v[58:61]
	v_mfma_f32_16x16x32_bf16 v[50:53], v[144:147], v[222:225], v[50:53]
	v_mfma_f32_16x16x32_bf16 v[42:45], v[158:161], v[222:225], v[42:45]
	v_mfma_f32_16x16x32_bf16 v[34:37], v[144:147], v[230:233], v[34:37]
	v_mfma_f32_16x16x32_bf16 v[26:29], v[158:161], v[230:233], v[26:29]
	v_mfma_f32_16x16x32_bf16 v[18:21], v[144:147], v[238:241], v[18:21]
	v_mfma_f32_16x16x32_bf16 v[10:13], v[158:161], v[238:241], v[10:13]
	s_setprio 0
	s_setprio 1
	v_mfma_f32_16x16x32_bf16 v[54:57], v[162:165], v[188:191], v[54:57]
	v_mfma_f32_16x16x32_bf16 v[46:49], v[180:183], v[188:191], v[46:49]
	v_mfma_f32_16x16x32_bf16 v[38:41], v[162:165], v[196:199], v[38:41]
	v_mfma_f32_16x16x32_bf16 v[30:33], v[180:183], v[196:199], v[30:33]
	v_mfma_f32_16x16x32_bf16 v[22:25], v[162:165], v[226:229], v[22:25]
	v_mfma_f32_16x16x32_bf16 v[14:17], v[180:183], v[226:229], v[14:17]
	v_mfma_f32_16x16x32_bf16 v[6:9], v[162:165], v[234:237], v[6:9]
	v_mfma_f32_16x16x32_bf16 v[2:5], v[180:183], v[234:237], v[2:5]
	v_mfma_f32_16x16x32_bf16 v[54:57], v[176:179], v[192:195], v[54:57]
	v_mfma_f32_16x16x32_bf16 v[46:49], v[184:187], v[192:195], v[46:49]
	v_mfma_f32_16x16x32_bf16 v[38:41], v[176:179], v[222:225], v[38:41]
	v_mfma_f32_16x16x32_bf16 v[30:33], v[184:187], v[222:225], v[30:33]
	s_setprio 2
	s_barrier
	v_mfma_f32_16x16x32_bf16 v[22:25], v[176:179], v[230:233], v[22:25]
	v_mfma_f32_16x16x32_bf16 v[14:17], v[184:187], v[230:233], v[14:17]
	v_mfma_f32_16x16x32_bf16 v[6:9], v[176:179], v[238:241], v[6:9]
	v_mfma_f32_16x16x32_bf16 v[2:5], v[184:187], v[238:241], v[2:5]
	s_setprio 0
	s_add_i32 s49, 0, 0x18000
	v_add_u32_e32 v153, s49, v149
	s_add_i32 s69, 0, 0x1c000
	ds_read_b128 v[140:143], v153
	ds_read_b128 v[144:147], v153 offset:1024
	ds_read_b128 v[154:157], v153 offset:2048
	ds_read_b128 v[158:161], v153 offset:3072
	v_add_u32_e32 v153, s69, v149
	ds_read_b128 v[162:165], v153
	ds_read_b128 v[176:179], v153 offset:1024
	ds_read_b128 v[180:183], v153 offset:2048
	ds_read_b128 v[184:187], v153 offset:3072
	s_add_u32 s26, s26, 0x80000
	s_addc_u32 s27, s27, 0
	s_mov_b32 m0, s37
	v_lshl_add_u64 v[246:247], s[26:27], 0, v[130:131]
	ds_read_b128 v[188:191], v152 offset:32768
	ds_read_b128 v[192:195], v152 offset:33792
	ds_read_b128 v[196:199], v152 offset:34816
	ds_read_b128 v[222:225], v152 offset:35840
	ds_read_b128 v[226:229], v152 offset:36864
	ds_read_b128 v[230:233], v152 offset:37888
	ds_read_b128 v[234:237], v152 offset:38912
	ds_read_b128 v[238:241], v152 offset:39936
	global_load_lds_dwordx4 v[246:247], off
	v_lshl_add_u64 v[246:247], s[26:27], 0, v[132:133]
	s_mov_b32 m0, s38
	s_nop 0
	global_load_lds_dwordx4 v[246:247], off
	s_waitcnt vmcnt(8)
	s_waitcnt lgkmcnt(0)
	s_barrier
	s_setprio 1
	s_waitcnt lgkmcnt(0)
	v_mfma_f32_16x16x32_bf16 v[126:129], v[140:143], v[188:191], v[126:129]
	v_mfma_f32_16x16x32_bf16 v[122:125], v[154:157], v[188:191], v[122:125]
	v_mfma_f32_16x16x32_bf16 v[114:117], v[140:143], v[196:199], v[114:117]
	v_mfma_f32_16x16x32_bf16 v[106:109], v[154:157], v[196:199], v[106:109]
	v_mfma_f32_16x16x32_bf16 v[98:101], v[140:143], v[226:229], v[98:101]
	v_mfma_f32_16x16x32_bf16 v[90:93], v[154:157], v[226:229], v[90:93]
	v_mfma_f32_16x16x32_bf16 v[82:85], v[140:143], v[234:237], v[82:85]
	v_mfma_f32_16x16x32_bf16 v[74:77], v[154:157], v[234:237], v[74:77]
	v_mfma_f32_16x16x32_bf16 v[126:129], v[144:147], v[192:195], v[126:129]
	v_mfma_f32_16x16x32_bf16 v[122:125], v[158:161], v[192:195], v[122:125]
	v_mfma_f32_16x16x32_bf16 v[114:117], v[144:147], v[222:225], v[114:117]
	v_mfma_f32_16x16x32_bf16 v[106:109], v[158:161], v[222:225], v[106:109]
	v_mfma_f32_16x16x32_bf16 v[98:101], v[144:147], v[230:233], v[98:101]
	v_mfma_f32_16x16x32_bf16 v[90:93], v[158:161], v[230:233], v[90:93]
	v_mfma_f32_16x16x32_bf16 v[82:85], v[144:147], v[238:241], v[82:85]
	v_mfma_f32_16x16x32_bf16 v[74:77], v[158:161], v[238:241], v[74:77]
	s_setprio 0
	s_setprio 1
	v_mfma_f32_16x16x32_bf16 v[118:121], v[162:165], v[188:191], v[118:121]
	v_mfma_f32_16x16x32_bf16 v[110:113], v[180:183], v[188:191], v[110:113]
	v_mfma_f32_16x16x32_bf16 v[102:105], v[162:165], v[196:199], v[102:105]
	v_mfma_f32_16x16x32_bf16 v[94:97], v[180:183], v[196:199], v[94:97]
	v_mfma_f32_16x16x32_bf16 v[86:89], v[162:165], v[226:229], v[86:89]
	v_mfma_f32_16x16x32_bf16 v[78:81], v[180:183], v[226:229], v[78:81]
	v_mfma_f32_16x16x32_bf16 v[70:73], v[162:165], v[234:237], v[70:73]
	v_mfma_f32_16x16x32_bf16 v[66:69], v[180:183], v[234:237], v[66:69]
	v_mfma_f32_16x16x32_bf16 v[118:121], v[176:179], v[192:195], v[118:121]
	v_mfma_f32_16x16x32_bf16 v[110:113], v[184:187], v[192:195], v[110:113]
	v_mfma_f32_16x16x32_bf16 v[102:105], v[176:179], v[222:225], v[102:105]
	v_mfma_f32_16x16x32_bf16 v[94:97], v[184:187], v[222:225], v[94:97]
	s_setprio 2
	s_barrier
; #define PG8_STAGE(bufoff, gbase, voff) do { _Pragma("unroll") for (int _i = 0; _i < 2; ++_i) \
;         __builtin_amdgcn_global_load_lds((const unsigned*)((const char*)(gbase) + (voff)[_i]), (LAS unsigned*)(lds + (bufoff) + ldsw + _i * 8192), 16, 0, 0); } while (0)
; #define PG8_LDA(dst, b, h) do { _Pragma("unroll") for (int m = 0; m < 4; ++m) _Pragma("unroll") for (int k = 0; k < 2; ++k) dst[m][k] = *(const LAS bf16x8*)(lds + PG8_SA(b, h) + aoff + m * 2048 + k * 1024); } while (0)
; #define PG8_MMA(ai, bj, At, Bt) do { __builtin_amdgcn_s_setprio(1); _Pragma("unroll") for (int m = 0; m < 4; ++m) _Pragma("unroll") for (int n = 0; n < 2; ++n) _Pragma("unroll") for (int k = 0; k < 2; ++k) \
;         acc[ai][bj][m][n] = __builtin_amdgcn_mfma_f32_16x16x32_bf16(Bt[n][k], At[m][k], acc[ai][bj][m][n], 0, 0, 0); __builtin_amdgcn_s_setprio(0); } while (0)
; #define PG8_WAIT_V(n) asm volatile("s_waitcnt vmcnt(" #n ")" ::: "memory")
; #define PG8_WAIT_L(n) asm volatile("s_waitcnt lgkmcnt(" #n ")" ::: "memory")
; #define PG8_BAR __builtin_amdgcn_s_barrier()
; #define PG8_SCHED __builtin_amdgcn_sched_barrier(0)
; template <class Epi>
; __device__ __forceinline__ void gemm_phase(LAS unsigned char* lds, const Sched& S, const Epi& E) {
;     ...
;             PG8_WAIT_V(8); PG8_WAIT_L(0); PG8_BAR; PG8_MMA(0, 0, At, B0); PG8_MMA(0, 1, At, B1); PG8_BAR; PG8_SCHED;
;             PG8_LDA(At, 1, 1); PG8_STAGE(PG8_SB(1, 0), b3, voffB); PG8_STAGE(PG8_SB(1, 1), b3 + hstepB, voffB); PG8_STAGE(PG8_SA(1, 0), a3, voffA);
;             PG8_WAIT_V(8); PG8_WAIT_L(0); PG8_BAR; PG8_MMA(1, 0, At, B0); PG8_MMA(1, 1, At, B1); PG8_BAR; PG8_SCHED;
;         }
;         if (wr == 0) PG8_BAR;
	v_mfma_f32_16x16x32_bf16 v[86:89], v[176:179], v[230:233], v[86:89]
	v_mfma_f32_16x16x32_bf16 v[78:81], v[184:187], v[230:233], v[78:81]
	v_mfma_f32_16x16x32_bf16 v[70:73], v[176:179], v[238:241], v[70:73]
	v_mfma_f32_16x16x32_bf16 v[66:69], v[184:187], v[238:241], v[66:69]
	s_setprio 0
	s_add_i32 s26, s49, s35
	v_lshl_add_u64 v[166:167], v[166:167], 0, s[0:1]
	s_mov_b32 m0, s26
	ds_read_b128 v[188:191], v152 offset:49152
	ds_read_b128 v[192:195], v152 offset:50176
	ds_read_b128 v[196:199], v152 offset:51200
	ds_read_b128 v[222:225], v152 offset:52224
	ds_read_b128 v[226:229], v152 offset:53248
	ds_read_b128 v[230:233], v152 offset:54272
	ds_read_b128 v[234:237], v152 offset:55296
	ds_read_b128 v[238:241], v152 offset:56320
	global_load_lds_dwordx4 v[166:167], off
	s_add_i32 m0, s26, 0x2000
	s_add_u32 s24, s24, 0x80080
	v_lshl_add_u64 v[166:167], v[200:201], 0, s[0:1]
	s_addc_u32 s25, s25, 0
	s_add_i32 s26, s69, s35
	global_load_lds_dwordx4 v[166:167], off
	v_lshl_add_u64 v[166:167], s[24:25], 0, v[168:169]
	s_mov_b32 m0, s26
	s_nop 0
	global_load_lds_dwordx4 v[166:167], off
	v_lshl_add_u64 v[166:167], s[24:25], 0, v[134:135]
	s_add_i32 m0, s26, 0x2000
	s_nop 0
	global_load_lds_dwordx4 v[166:167], off
	v_lshl_add_u64 v[166:167], v[242:243], 0, s[0:1]
	s_mov_b32 m0, s39
	s_nop 0
	global_load_lds_dwordx4 v[166:167], off
	v_lshl_add_u64 v[166:167], v[244:245], 0, s[0:1]
	s_mov_b32 m0, s59
	s_nop 0
	global_load_lds_dwordx4 v[166:167], off
	s_waitcnt vmcnt(8)
	s_waitcnt lgkmcnt(0)
	s_barrier
	s_setprio 1
	s_waitcnt lgkmcnt(0)
	v_mfma_f32_16x16x32_bf16 v[62:65], v[140:143], v[188:191], v[62:65]
	v_mfma_f32_16x16x32_bf16 v[58:61], v[154:157], v[188:191], v[58:61]
	v_mfma_f32_16x16x32_bf16 v[50:53], v[140:143], v[196:199], v[50:53]
	v_mfma_f32_16x16x32_bf16 v[42:45], v[154:157], v[196:199], v[42:45]
	v_mfma_f32_16x16x32_bf16 v[34:37], v[140:143], v[226:229], v[34:37]
	v_mfma_f32_16x16x32_bf16 v[26:29], v[154:157], v[226:229], v[26:29]
	v_mfma_f32_16x16x32_bf16 v[18:21], v[140:143], v[234:237], v[18:21]
	v_mfma_f32_16x16x32_bf16 v[10:13], v[154:157], v[234:237], v[10:13]
	v_mfma_f32_16x16x32_bf16 v[62:65], v[144:147], v[192:195], v[62:65]
	v_mfma_f32_16x16x32_bf16 v[58:61], v[158:161], v[192:195], v[58:61]
	v_mfma_f32_16x16x32_bf16 v[50:53], v[144:147], v[222:225], v[50:53]
	v_mfma_f32_16x16x32_bf16 v[42:45], v[158:161], v[222:225], v[42:45]
	v_mfma_f32_16x16x32_bf16 v[34:37], v[144:147], v[230:233], v[34:37]
	v_mfma_f32_16x16x32_bf16 v[26:29], v[158:161], v[230:233], v[26:29]
	v_mfma_f32_16x16x32_bf16 v[18:21], v[144:147], v[238:241], v[18:21]
	v_mfma_f32_16x16x32_bf16 v[10:13], v[158:161], v[238:241], v[10:13]
	s_setprio 0
	s_setprio 1
	v_mfma_f32_16x16x32_bf16 v[54:57], v[162:165], v[188:191], v[54:57]
	v_mfma_f32_16x16x32_bf16 v[46:49], v[180:183], v[188:191], v[46:49]
	v_mfma_f32_16x16x32_bf16 v[38:41], v[162:165], v[196:199], v[38:41]
	v_mfma_f32_16x16x32_bf16 v[30:33], v[180:183], v[196:199], v[30:33]
	v_mfma_f32_16x16x32_bf16 v[22:25], v[162:165], v[226:229], v[22:25]
	v_mfma_f32_16x16x32_bf16 v[14:17], v[180:183], v[226:229], v[14:17]
	v_mfma_f32_16x16x32_bf16 v[6:9], v[162:165], v[234:237], v[6:9]
	v_mfma_f32_16x16x32_bf16 v[2:5], v[180:183], v[234:237], v[2:5]
	v_mfma_f32_16x16x32_bf16 v[54:57], v[176:179], v[192:195], v[54:57]
	v_mfma_f32_16x16x32_bf16 v[46:49], v[184:187], v[192:195], v[46:49]
	v_mfma_f32_16x16x32_bf16 v[38:41], v[176:179], v[222:225], v[38:41]
	v_mfma_f32_16x16x32_bf16 v[30:33], v[184:187], v[222:225], v[30:33]
	s_setprio 2
	s_barrier
	v_mfma_f32_16x16x32_bf16 v[22:25], v[176:179], v[230:233], v[22:25]
	v_mfma_f32_16x16x32_bf16 v[14:17], v[184:187], v[230:233], v[14:17]
	v_mfma_f32_16x16x32_bf16 v[6:9], v[176:179], v[238:241], v[6:9]
	v_mfma_f32_16x16x32_bf16 v[2:5], v[184:187], v[238:241], v[2:5]
	s_setprio 0
	s_add_i32 s68, s68, 2
	s_add_u32 s22, s22, 0x100
	s_addc_u32 s23, s23, 0
	s_add_u32 s9, s9, 0x100
	s_addc_u32 s11, s11, 0
	s_cmp_gt_u32 s68, 29
	s_cbranch_scc0 .LBB0_735
	s_and_b64 vcc, exec, s[6:7]
	s_cbranch_vccz .LBB0_738
	s_barrier

; #define PG8_STAGE(bufoff, gbase, voff) do { _Pragma("unroll") for (int _i = 0; _i < 2; ++_i) \
;         __builtin_amdgcn_global_load_lds((const unsigned*)((const char*)(gbase) + (voff)[_i]), (LAS unsigned*)(lds + (bufoff) + ldsw + _i * 8192), 16, 0, 0); } while (0)
; #define PG8_LDA(dst, b, h) do { _Pragma("unroll") for (int m = 0; m < 4; ++m) _Pragma("unroll") for (int k = 0; k < 2; ++k) dst[m][k] = *(const LAS bf16x8*)(lds + PG8_SA(b, h) + aoff + m * 2048 + k * 1024); } while (0)
; #define PG8_LDB(dst, b, h) do { _Pragma("unroll") for (int n = 0; n < 2; ++n) _Pragma("unroll") for (int k = 0; k < 2; ++k) dst[n][k] = *(const LAS bf16x8*)(lds + PG8_SB(b, h) + boff + n * 2048 + k * 1024); } while (0)
; #define PG8_MMA(ai, bj, At, Bt) do { __builtin_amdgcn_s_setprio(1); _Pragma("unroll") for (int m = 0; m < 4; ++m) _Pragma("unroll") for (int n = 0; n < 2; ++n) _Pragma("unroll") for (int k = 0; k < 2; ++k) \
;         acc[ai][bj][m][n] = __builtin_amdgcn_mfma_f32_16x16x32_bf16(Bt[n][k], At[m][k], acc[ai][bj][m][n], 0, 0, 0); __builtin_amdgcn_s_setprio(0); } while (0)
; #define PG8_WAIT_V(n) asm volatile("s_waitcnt vmcnt(" #n ")" ::: "memory")
; #define PG8_WAIT_L(n) asm volatile("s_waitcnt lgkmcnt(" #n ")" ::: "memory")
; #define PG8_BAR __builtin_amdgcn_s_barrier()
; #define PG8_SCHED __builtin_amdgcn_sched_barrier(0)
; template <class Epi>
; __device__ __forceinline__ void gemm_phase(LAS unsigned char* lds, const Sched& S, const Epi& E) {
;     ...
;             const bool last = (t == nt - 2);
;             const char* a1 = cA + (size_t)(t + 1) * kstep;
;             const char* a2 = last ? nA : cA + (size_t)(t + 2) * kstep; const char* b2 = last ? nB : cB + (size_t)(t + 2) * kstep;
;             const char* a3 = a2 + kstep; const char* b3 = b2 + kstep;
;             PG8_LDB(B0, 0, 0); PG8_LDB(B1, 0, 1); PG8_SCHED; PG8_LDA(At, 0, 0); PG8_STAGE(PG8_SA(1, 1), a1 + hstepA, voffA);
;             PG8_WAIT_V(8); PG8_WAIT_L(0); PG8_BAR; PG8_MMA(0, 0, At, B0); PG8_MMA(0, 1, At, B1); PG8_BAR; PG8_SCHED;
;             PG8_LDA(At, 0, 1); PG8_STAGE(PG8_SB(0, 0), b2, voffB); PG8_STAGE(PG8_SB(0, 1), b2 + hstepB, voffB); PG8_STAGE(PG8_SA(0, 0), a2, voffA);
.LBB0_1389:
	s_add_i32 s95, s22, 2
	s_add_u32 s23, s20, 0xfff80080
	s_addc_u32 s24, s21, -1
	s_add_i32 s49, 0, 0x10000
	s_cmp_eq_u32 s69, s22
	s_cselect_b32 s25, s9, s24
	s_cselect_b32 s24, s13, s23
	s_cselect_b32 s23, s26, s94
	s_cselect_b32 s22, s27, s82
	s_add_i32 s88, 0, 0x14000
	v_add_u32_e32 v142, s49, v179
	v_add_u32_e32 v176, s88, v179
	ds_read_b128 v[130:133], v142
	ds_read_b128 v[134:137], v142 offset:1024
	ds_read_b128 v[138:141], v142 offset:2048
	ds_read_b128 v[142:145], v142 offset:3072
	ds_read_b128 v[160:163], v176
	ds_read_b128 v[164:167], v176 offset:1024
	ds_read_b128 v[182:185], v176 offset:2048
	ds_read_b128 v[186:189], v176 offset:3072
	v_lshl_add_u64 v[176:177], s[20:21], 0, v[156:157]
	s_add_i32 m0, s35, 0xc000
	ds_read_b128 v[190:193], v181
	ds_read_b128 v[194:197], v181 offset:1024
	ds_read_b128 v[198:201], v181 offset:2048
	ds_read_b128 v[222:225], v181 offset:3072
	ds_read_b128 v[226:229], v181 offset:4096
	ds_read_b128 v[230:233], v181 offset:5120
	ds_read_b128 v[234:237], v181 offset:6144
	ds_read_b128 v[238:241], v181 offset:7168
	global_load_lds_dwordx4 v[176:177], off
	v_lshl_add_u64 v[176:177], s[20:21], 0, v[158:159]
	s_add_i32 m0, s35, 0xe000
	s_nop 0
	global_load_lds_dwordx4 v[176:177], off
	s_waitcnt vmcnt(8)
	s_waitcnt lgkmcnt(0)
	s_barrier
	s_setprio 1
	s_waitcnt lgkmcnt(0)
	v_mfma_f32_16x16x32_bf16 v[126:129], v[130:133], v[190:193], v[126:129]
	v_mfma_f32_16x16x32_bf16 v[122:125], v[138:141], v[190:193], v[122:125]
	v_mfma_f32_16x16x32_bf16 v[110:113], v[130:133], v[198:201], v[110:113]
	v_mfma_f32_16x16x32_bf16 v[106:109], v[138:141], v[198:201], v[106:109]
	v_mfma_f32_16x16x32_bf16 v[94:97], v[130:133], v[226:229], v[94:97]
	v_mfma_f32_16x16x32_bf16 v[90:93], v[138:141], v[226:229], v[90:93]
	v_mfma_f32_16x16x32_bf16 v[78:81], v[130:133], v[234:237], v[78:81]
	v_mfma_f32_16x16x32_bf16 v[74:77], v[138:141], v[234:237], v[74:77]
	v_mfma_f32_16x16x32_bf16 v[126:129], v[134:137], v[194:197], v[126:129]
	v_mfma_f32_16x16x32_bf16 v[122:125], v[142:145], v[194:197], v[122:125]
	v_mfma_f32_16x16x32_bf16 v[110:113], v[134:137], v[222:225], v[110:113]
	v_mfma_f32_16x16x32_bf16 v[106:109], v[142:145], v[222:225], v[106:109]
	v_mfma_f32_16x16x32_bf16 v[94:97], v[134:137], v[230:233], v[94:97]
	v_mfma_f32_16x16x32_bf16 v[90:93], v[142:145], v[230:233], v[90:93]
	v_mfma_f32_16x16x32_bf16 v[78:81], v[134:137], v[238:241], v[78:81]
	v_mfma_f32_16x16x32_bf16 v[74:77], v[142:145], v[238:241], v[74:77]
	s_setprio 0
	s_setprio 1
	v_mfma_f32_16x16x32_bf16 v[118:121], v[160:163], v[190:193], v[118:121]
	v_mfma_f32_16x16x32_bf16 v[114:117], v[182:185], v[190:193], v[114:117]
	v_mfma_f32_16x16x32_bf16 v[102:105], v[160:163], v[198:201], v[102:105]
	v_mfma_f32_16x16x32_bf16 v[98:101], v[182:185], v[198:201], v[98:101]
	v_mfma_f32_16x16x32_bf16 v[86:89], v[160:163], v[226:229], v[86:89]
	v_mfma_f32_16x16x32_bf16 v[82:85], v[182:185], v[226:229], v[82:85]
	v_mfma_f32_16x16x32_bf16 v[70:73], v[160:163], v[234:237], v[70:73]
	v_mfma_f32_16x16x32_bf16 v[66:69], v[182:185], v[234:237], v[66:69]
	v_mfma_f32_16x16x32_bf16 v[118:121], v[164:167], v[194:197], v[118:121]
	v_mfma_f32_16x16x32_bf16 v[114:117], v[186:189], v[194:197], v[114:117]
	v_mfma_f32_16x16x32_bf16 v[102:105], v[164:167], v[222:225], v[102:105]
	v_mfma_f32_16x16x32_bf16 v[98:101], v[186:189], v[222:225], v[98:101]
	s_setprio 2
	s_barrier
	v_mfma_f32_16x16x32_bf16 v[86:89], v[164:167], v[230:233], v[86:89]
	v_mfma_f32_16x16x32_bf16 v[82:85], v[186:189], v[230:233], v[82:85]
	v_mfma_f32_16x16x32_bf16 v[70:73], v[164:167], v[238:241], v[70:73]
	v_mfma_f32_16x16x32_bf16 v[66:69], v[186:189], v[238:241], v[66:69]
	s_setprio 0
	s_add_i32 s49, s49, s34
	v_lshl_add_u64 v[176:177], s[22:23], 0, v[168:169]
	s_mov_b32 m0, s49
	ds_read_b128 v[190:193], v181 offset:16384
	ds_read_b128 v[194:197], v181 offset:17408
	ds_read_b128 v[198:201], v181 offset:18432
	ds_read_b128 v[222:225], v181 offset:19456
	ds_read_b128 v[226:229], v181 offset:20480
	ds_read_b128 v[230:233], v181 offset:21504
	ds_read_b128 v[234:237], v181 offset:22528
	ds_read_b128 v[238:241], v181 offset:23552
	global_load_lds_dwordx4 v[176:177], off
	s_add_i32 m0, s49, 0x2000
	s_add_u32 s96, s22, 0x80000
	v_lshl_add_u64 v[242:243], s[22:23], 0, v[146:147]
	s_addc_u32 s97, s23, 0
	s_add_i32 s49, s88, s34
	global_load_lds_dwordx4 v[242:243], off
	v_lshl_add_u64 v[244:245], s[96:97], 0, v[168:169]
	s_mov_b32 m0, s49
	v_lshl_add_u64 v[246:247], s[24:25], 0, v[146:147]
	global_load_lds_dwordx4 v[244:245], off
	v_lshl_add_u64 v[244:245], s[96:97], 0, v[146:147]
	s_add_i32 m0, s49, 0x2000
	s_nop 0
	global_load_lds_dwordx4 v[244:245], off
	v_lshl_add_u64 v[244:245], s[24:25], 0, v[168:169]
	s_mov_b32 m0, s35
	s_nop 0
	global_load_lds_dwordx4 v[244:245], off
	s_mov_b32 m0, s36
	s_nop 0
	global_load_lds_dwordx4 v[246:247], off
	s_waitcnt vmcnt(8)
	s_waitcnt lgkmcnt(0)
	s_barrier
; #define PG8_STAGE(bufoff, gbase, voff) do { _Pragma("unroll") for (int _i = 0; _i < 2; ++_i) \
;         __builtin_amdgcn_global_load_lds((const unsigned*)((const char*)(gbase) + (voff)[_i]), (LAS unsigned*)(lds + (bufoff) + ldsw + _i * 8192), 16, 0, 0); } while (0)
; #define PG8_LDA(dst, b, h) do { _Pragma("unroll") for (int m = 0; m < 4; ++m) _Pragma("unroll") for (int k = 0; k < 2; ++k) dst[m][k] = *(const LAS bf16x8*)(lds + PG8_SA(b, h) + aoff + m * 2048 + k * 1024); } while (0)
; #define PG8_LDB(dst, b, h) do { _Pragma("unroll") for (int n = 0; n < 2; ++n) _Pragma("unroll") for (int k = 0; k < 2; ++k) dst[n][k] = *(const LAS bf16x8*)(lds + PG8_SB(b, h) + boff + n * 2048 + k * 1024); } while (0)
; #define PG8_MMA(ai, bj, At, Bt) do { __builtin_amdgcn_s_setprio(1); _Pragma("unroll") for (int m = 0; m < 4; ++m) _Pragma("unroll") for (int n = 0; n < 2; ++n) _Pragma("unroll") for (int k = 0; k < 2; ++k) \
;         acc[ai][bj][m][n] = __builtin_amdgcn_mfma_f32_16x16x32_bf16(Bt[n][k], At[m][k], acc[ai][bj][m][n], 0, 0, 0); __builtin_amdgcn_s_setprio(0); } while (0)
; #define PG8_WAIT_V(n) asm volatile("s_waitcnt vmcnt(" #n ")" ::: "memory")
; #define PG8_WAIT_L(n) asm volatile("s_waitcnt lgkmcnt(" #n ")" ::: "memory")
; #define PG8_BAR __builtin_amdgcn_s_barrier()
; #define PG8_SCHED __builtin_amdgcn_sched_barrier(0)
; template <class Epi>
; __device__ __forceinline__ void gemm_phase(LAS unsigned char* lds, const Sched& S, const Epi& E) {
;     ...
;             PG8_WAIT_V(8); PG8_WAIT_L(0); PG8_BAR; PG8_MMA(1, 0, At, B0); PG8_MMA(1, 1, At, B1); PG8_BAR; PG8_SCHED;
;             PG8_LDB(B0, 1, 0); PG8_LDB(B1, 1, 1); PG8_SCHED; PG8_LDA(At, 1, 0); PG8_STAGE(PG8_SA(0, 1), a2 + hstepA, voffA);
;             PG8_WAIT_V(8); PG8_WAIT_L(0); PG8_BAR; PG8_MMA(0, 0, At, B0); PG8_MMA(0, 1, At, B1); PG8_BAR; PG8_SCHED;
	s_setprio 1
	s_waitcnt lgkmcnt(0)
	v_mfma_f32_16x16x32_bf16 v[62:65], v[130:133], v[190:193], v[62:65]
	v_mfma_f32_16x16x32_bf16 v[58:61], v[138:141], v[190:193], v[58:61]
	v_mfma_f32_16x16x32_bf16 v[46:49], v[130:133], v[198:201], v[46:49]
	v_mfma_f32_16x16x32_bf16 v[42:45], v[138:141], v[198:201], v[42:45]
	v_mfma_f32_16x16x32_bf16 v[30:33], v[130:133], v[226:229], v[30:33]
	v_mfma_f32_16x16x32_bf16 v[26:29], v[138:141], v[226:229], v[26:29]
	v_mfma_f32_16x16x32_bf16 v[14:17], v[130:133], v[234:237], v[14:17]
	v_mfma_f32_16x16x32_bf16 v[10:13], v[138:141], v[234:237], v[10:13]
	v_mfma_f32_16x16x32_bf16 v[62:65], v[134:137], v[194:197], v[62:65]
	v_mfma_f32_16x16x32_bf16 v[58:61], v[142:145], v[194:197], v[58:61]
	v_mfma_f32_16x16x32_bf16 v[46:49], v[134:137], v[222:225], v[46:49]
	v_mfma_f32_16x16x32_bf16 v[42:45], v[142:145], v[222:225], v[42:45]
	v_mfma_f32_16x16x32_bf16 v[30:33], v[134:137], v[230:233], v[30:33]
	v_mfma_f32_16x16x32_bf16 v[26:29], v[142:145], v[230:233], v[26:29]
	v_mfma_f32_16x16x32_bf16 v[14:17], v[134:137], v[238:241], v[14:17]
	v_mfma_f32_16x16x32_bf16 v[10:13], v[142:145], v[238:241], v[10:13]
	s_setprio 0
	s_setprio 1
	v_mfma_f32_16x16x32_bf16 v[54:57], v[160:163], v[190:193], v[54:57]
	v_mfma_f32_16x16x32_bf16 v[50:53], v[182:185], v[190:193], v[50:53]
	v_mfma_f32_16x16x32_bf16 v[38:41], v[160:163], v[198:201], v[38:41]
	v_mfma_f32_16x16x32_bf16 v[34:37], v[182:185], v[198:201], v[34:37]
	v_mfma_f32_16x16x32_bf16 v[22:25], v[160:163], v[226:229], v[22:25]
	v_mfma_f32_16x16x32_bf16 v[18:21], v[182:185], v[226:229], v[18:21]
	v_mfma_f32_16x16x32_bf16 v[6:9], v[160:163], v[234:237], v[6:9]
	v_mfma_f32_16x16x32_bf16 v[2:5], v[182:185], v[234:237], v[2:5]
	v_mfma_f32_16x16x32_bf16 v[54:57], v[164:167], v[194:197], v[54:57]
	v_mfma_f32_16x16x32_bf16 v[50:53], v[186:189], v[194:197], v[50:53]
	v_mfma_f32_16x16x32_bf16 v[38:41], v[164:167], v[222:225], v[38:41]
	v_mfma_f32_16x16x32_bf16 v[34:37], v[186:189], v[222:225], v[34:37]
	s_setprio 2
	s_barrier
	v_mfma_f32_16x16x32_bf16 v[22:25], v[164:167], v[230:233], v[22:25]
	v_mfma_f32_16x16x32_bf16 v[18:21], v[186:189], v[230:233], v[18:21]
	v_mfma_f32_16x16x32_bf16 v[6:9], v[164:167], v[238:241], v[6:9]
	v_mfma_f32_16x16x32_bf16 v[2:5], v[186:189], v[238:241], v[2:5]
	s_setprio 0
	s_add_i32 s49, 0, 0x18000
	s_add_i32 s88, 0, 0x1c000
	v_add_u32_e32 v142, s49, v179
	v_add_u32_e32 v186, s88, v179
	ds_read_b128 v[130:133], v142
	ds_read_b128 v[134:137], v142 offset:1024
	ds_read_b128 v[138:141], v142 offset:2048
	ds_read_b128 v[142:145], v142 offset:3072
	ds_read_b128 v[160:163], v186
	ds_read_b128 v[164:167], v186 offset:1024
	ds_read_b128 v[182:185], v186 offset:2048
	ds_read_b128 v[186:189], v186 offset:3072
	s_add_u32 s24, s24, 0x80000
	s_addc_u32 s25, s25, 0
	s_mov_b32 m0, s37
	v_lshl_add_u64 v[248:249], s[24:25], 0, v[168:169]
	ds_read_b128 v[190:193], v181 offset:32768
	ds_read_b128 v[194:197], v181 offset:33792
	ds_read_b128 v[198:201], v181 offset:34816
	ds_read_b128 v[222:225], v181 offset:35840
	ds_read_b128 v[226:229], v181 offset:36864
	ds_read_b128 v[230:233], v181 offset:37888
	ds_read_b128 v[234:237], v181 offset:38912
	ds_read_b128 v[238:241], v181 offset:39936
	global_load_lds_dwordx4 v[248:249], off
	v_lshl_add_u64 v[248:249], s[24:25], 0, v[146:147]
	s_mov_b32 m0, s38
	s_nop 0
	global_load_lds_dwordx4 v[248:249], off
	s_waitcnt vmcnt(8)
	s_waitcnt lgkmcnt(0)
	s_barrier
	s_setprio 1
	s_waitcnt lgkmcnt(0)
	v_mfma_f32_16x16x32_bf16 v[126:129], v[130:133], v[190:193], v[126:129]
	v_mfma_f32_16x16x32_bf16 v[122:125], v[138:141], v[190:193], v[122:125]
	v_mfma_f32_16x16x32_bf16 v[110:113], v[130:133], v[198:201], v[110:113]
	v_mfma_f32_16x16x32_bf16 v[106:109], v[138:141], v[198:201], v[106:109]
	v_mfma_f32_16x16x32_bf16 v[94:97], v[130:133], v[226:229], v[94:97]
	v_mfma_f32_16x16x32_bf16 v[90:93], v[138:141], v[226:229], v[90:93]
	v_mfma_f32_16x16x32_bf16 v[78:81], v[130:133], v[234:237], v[78:81]
	v_mfma_f32_16x16x32_bf16 v[74:77], v[138:141], v[234:237], v[74:77]
	v_mfma_f32_16x16x32_bf16 v[126:129], v[134:137], v[194:197], v[126:129]
	v_mfma_f32_16x16x32_bf16 v[122:125], v[142:145], v[194:197], v[122:125]
	v_mfma_f32_16x16x32_bf16 v[110:113], v[134:137], v[222:225], v[110:113]
	v_mfma_f32_16x16x32_bf16 v[106:109], v[142:145], v[222:225], v[106:109]
	v_mfma_f32_16x16x32_bf16 v[94:97], v[134:137], v[230:233], v[94:97]
	v_mfma_f32_16x16x32_bf16 v[90:93], v[142:145], v[230:233], v[90:93]
	v_mfma_f32_16x16x32_bf16 v[78:81], v[134:137], v[238:241], v[78:81]
	v_mfma_f32_16x16x32_bf16 v[74:77], v[142:145], v[238:241], v[74:77]
	s_setprio 0
	s_setprio 1
	v_mfma_f32_16x16x32_bf16 v[118:121], v[160:163], v[190:193], v[118:121]
	v_mfma_f32_16x16x32_bf16 v[114:117], v[182:185], v[190:193], v[114:117]
	v_mfma_f32_16x16x32_bf16 v[102:105], v[160:163], v[198:201], v[102:105]
	v_mfma_f32_16x16x32_bf16 v[98:101], v[182:185], v[198:201], v[98:101]
	v_mfma_f32_16x16x32_bf16 v[86:89], v[160:163], v[226:229], v[86:89]
	v_mfma_f32_16x16x32_bf16 v[82:85], v[182:185], v[226:229], v[82:85]
	v_mfma_f32_16x16x32_bf16 v[70:73], v[160:163], v[234:237], v[70:73]
	v_mfma_f32_16x16x32_bf16 v[66:69], v[182:185], v[234:237], v[66:69]
	v_mfma_f32_16x16x32_bf16 v[118:121], v[164:167], v[194:197], v[118:121]
	v_mfma_f32_16x16x32_bf16 v[114:117], v[186:189], v[194:197], v[114:117]
	v_mfma_f32_16x16x32_bf16 v[102:105], v[164:167], v[222:225], v[102:105]
	v_mfma_f32_16x16x32_bf16 v[98:101], v[186:189], v[222:225], v[98:101]
	s_setprio 2
	s_barrier
; #define PG8_STAGE(bufoff, gbase, voff) do { _Pragma("unroll") for (int _i = 0; _i < 2; ++_i) \
;         __builtin_amdgcn_global_load_lds((const unsigned*)((const char*)(gbase) + (voff)[_i]), (LAS unsigned*)(lds + (bufoff) + ldsw + _i * 8192), 16, 0, 0); } while (0)
; #define PG8_LDA(dst, b, h) do { _Pragma("unroll") for (int m = 0; m < 4; ++m) _Pragma("unroll") for (int k = 0; k < 2; ++k) dst[m][k] = *(const LAS bf16x8*)(lds + PG8_SA(b, h) + aoff + m * 2048 + k * 1024); } while (0)
; #define PG8_MMA(ai, bj, At, Bt) do { __builtin_amdgcn_s_setprio(1); _Pragma("unroll") for (int m = 0; m < 4; ++m) _Pragma("unroll") for (int n = 0; n < 2; ++n) _Pragma("unroll") for (int k = 0; k < 2; ++k) \
;         acc[ai][bj][m][n] = __builtin_amdgcn_mfma_f32_16x16x32_bf16(Bt[n][k], At[m][k], acc[ai][bj][m][n], 0, 0, 0); __builtin_amdgcn_s_setprio(0); } while (0)
; #define PG8_WAIT_V(n) asm volatile("s_waitcnt vmcnt(" #n ")" ::: "memory")
; #define PG8_WAIT_L(n) asm volatile("s_waitcnt lgkmcnt(" #n ")" ::: "memory")
; #define PG8_BAR __builtin_amdgcn_s_barrier()
; #define PG8_SCHED __builtin_amdgcn_sched_barrier(0)
; template <class Epi>
; __device__ __forceinline__ void gemm_phase(LAS unsigned char* lds, const Sched& S, const Epi& E) {
;     ...
;             PG8_WAIT_V(8); PG8_WAIT_L(0); PG8_BAR; PG8_MMA(0, 0, At, B0); PG8_MMA(0, 1, At, B1); PG8_BAR; PG8_SCHED;
;             PG8_LDA(At, 1, 1); PG8_STAGE(PG8_SB(1, 0), b3, voffB); PG8_STAGE(PG8_SB(1, 1), b3 + hstepB, voffB); PG8_STAGE(PG8_SA(1, 0), a3, voffA);
;             PG8_WAIT_V(8); PG8_WAIT_L(0); PG8_BAR; PG8_MMA(1, 0, At, B0); PG8_MMA(1, 1, At, B1); PG8_BAR; PG8_SCHED;
;         }
;         if (wr == 0) PG8_BAR;
	v_mfma_f32_16x16x32_bf16 v[86:89], v[164:167], v[230:233], v[86:89]
	v_mfma_f32_16x16x32_bf16 v[82:85], v[186:189], v[230:233], v[82:85]
	v_mfma_f32_16x16x32_bf16 v[70:73], v[164:167], v[238:241], v[70:73]
	v_mfma_f32_16x16x32_bf16 v[66:69], v[186:189], v[238:241], v[66:69]
	s_setprio 0
	s_add_i32 s24, s49, s34
	v_lshl_add_u64 v[176:177], v[176:177], 0, s[0:1]
	s_mov_b32 m0, s24
	ds_read_b128 v[190:193], v181 offset:49152
	ds_read_b128 v[194:197], v181 offset:50176
	ds_read_b128 v[198:201], v181 offset:51200
	ds_read_b128 v[222:225], v181 offset:52224
	ds_read_b128 v[226:229], v181 offset:53248
	ds_read_b128 v[230:233], v181 offset:54272
	ds_read_b128 v[234:237], v181 offset:55296
	ds_read_b128 v[238:241], v181 offset:56320
	global_load_lds_dwordx4 v[176:177], off
	s_add_i32 m0, s24, 0x2000
	s_add_u32 s22, s22, 0x80080
	v_lshl_add_u64 v[176:177], v[242:243], 0, s[0:1]
	s_addc_u32 s23, s23, 0
	s_add_i32 s24, s88, s34
	global_load_lds_dwordx4 v[176:177], off
	v_lshl_add_u64 v[176:177], s[22:23], 0, v[168:169]
	s_mov_b32 m0, s24
	s_nop 0
	global_load_lds_dwordx4 v[176:177], off
	v_lshl_add_u64 v[176:177], s[22:23], 0, v[146:147]
	s_add_i32 m0, s24, 0x2000
	s_nop 0
	global_load_lds_dwordx4 v[176:177], off
	v_lshl_add_u64 v[176:177], v[244:245], 0, s[0:1]
	s_mov_b32 m0, s39
	s_nop 0
	global_load_lds_dwordx4 v[176:177], off
	v_lshl_add_u64 v[176:177], v[246:247], 0, s[0:1]
	s_mov_b32 m0, s59
	s_nop 0
	global_load_lds_dwordx4 v[176:177], off
	s_waitcnt vmcnt(8)
	s_waitcnt lgkmcnt(0)
	s_barrier
	s_setprio 1
	s_waitcnt lgkmcnt(0)
	v_mfma_f32_16x16x32_bf16 v[62:65], v[130:133], v[190:193], v[62:65]
	v_mfma_f32_16x16x32_bf16 v[58:61], v[138:141], v[190:193], v[58:61]
	v_mfma_f32_16x16x32_bf16 v[46:49], v[130:133], v[198:201], v[46:49]
	v_mfma_f32_16x16x32_bf16 v[42:45], v[138:141], v[198:201], v[42:45]
	v_mfma_f32_16x16x32_bf16 v[30:33], v[130:133], v[226:229], v[30:33]
	v_mfma_f32_16x16x32_bf16 v[26:29], v[138:141], v[226:229], v[26:29]
	v_mfma_f32_16x16x32_bf16 v[14:17], v[130:133], v[234:237], v[14:17]
	v_mfma_f32_16x16x32_bf16 v[10:13], v[138:141], v[234:237], v[10:13]
	v_mfma_f32_16x16x32_bf16 v[62:65], v[134:137], v[194:197], v[62:65]
	v_mfma_f32_16x16x32_bf16 v[58:61], v[142:145], v[194:197], v[58:61]
	v_mfma_f32_16x16x32_bf16 v[46:49], v[134:137], v[222:225], v[46:49]
	v_mfma_f32_16x16x32_bf16 v[42:45], v[142:145], v[222:225], v[42:45]
	v_mfma_f32_16x16x32_bf16 v[30:33], v[134:137], v[230:233], v[30:33]
	v_mfma_f32_16x16x32_bf16 v[26:29], v[142:145], v[230:233], v[26:29]
	v_mfma_f32_16x16x32_bf16 v[14:17], v[134:137], v[238:241], v[14:17]
	v_mfma_f32_16x16x32_bf16 v[10:13], v[142:145], v[238:241], v[10:13]
	s_setprio 0
	s_setprio 1
	v_mfma_f32_16x16x32_bf16 v[54:57], v[160:163], v[190:193], v[54:57]
	v_mfma_f32_16x16x32_bf16 v[50:53], v[182:185], v[190:193], v[50:53]
	v_mfma_f32_16x16x32_bf16 v[38:41], v[160:163], v[198:201], v[38:41]
	v_mfma_f32_16x16x32_bf16 v[34:37], v[182:185], v[198:201], v[34:37]
	v_mfma_f32_16x16x32_bf16 v[22:25], v[160:163], v[226:229], v[22:25]
	v_mfma_f32_16x16x32_bf16 v[18:21], v[182:185], v[226:229], v[18:21]
	v_mfma_f32_16x16x32_bf16 v[6:9], v[160:163], v[234:237], v[6:9]
	v_mfma_f32_16x16x32_bf16 v[2:5], v[182:185], v[234:237], v[2:5]
	v_mfma_f32_16x16x32_bf16 v[54:57], v[164:167], v[194:197], v[54:57]
	v_mfma_f32_16x16x32_bf16 v[50:53], v[186:189], v[194:197], v[50:53]
	v_mfma_f32_16x16x32_bf16 v[38:41], v[164:167], v[222:225], v[38:41]
	v_mfma_f32_16x16x32_bf16 v[34:37], v[186:189], v[222:225], v[34:37]
	s_setprio 2
	s_barrier
	v_mfma_f32_16x16x32_bf16 v[22:25], v[164:167], v[230:233], v[22:25]
	v_mfma_f32_16x16x32_bf16 v[18:21], v[186:189], v[230:233], v[18:21]
	v_mfma_f32_16x16x32_bf16 v[6:9], v[164:167], v[238:241], v[6:9]
	v_mfma_f32_16x16x32_bf16 v[2:5], v[186:189], v[238:241], v[2:5]
	s_setprio 0
	s_add_u32 s20, s20, 0x100
	s_addc_u32 s21, s21, 0
	s_add_u32 s82, s82, 0x100
	s_addc_u32 s94, s94, 0
	s_cmp_ge_i32 s95, s19
	s_mov_b32 s22, s95
	s_cbranch_scc0 .LBB0_1389
	s_and_b64 vcc, exec, s[6:7]
	s_cbranch_vccz .LBB0_1392
	s_barrier

; #define PG8_STAGE(bufoff, gbase, voff) do { _Pragma("unroll") for (int _i = 0; _i < 2; ++_i) \
;         __builtin_amdgcn_global_load_lds((const unsigned*)((const char*)(gbase) + (voff)[_i]), (LAS unsigned*)(lds + (bufoff) + ldsw + _i * 8192), 16, 0, 0); } while (0)
; #define PG8_LDA(dst, b, h) do { _Pragma("unroll") for (int m = 0; m < 4; ++m) _Pragma("unroll") for (int k = 0; k < 2; ++k) dst[m][k] = *(const LAS bf16x8*)(lds + PG8_SA(b, h) + aoff + m * 2048 + k * 1024); } while (0)
; #define PG8_LDB(dst, b, h) do { _Pragma("unroll") for (int n = 0; n < 2; ++n) _Pragma("unroll") for (int k = 0; k < 2; ++k) dst[n][k] = *(const LAS bf16x8*)(lds + PG8_SB(b, h) + boff + n * 2048 + k * 1024); } while (0)
; #define PG8_MMA(ai, bj, At, Bt) do { __builtin_amdgcn_s_setprio(1); _Pragma("unroll") for (int m = 0; m < 4; ++m) _Pragma("unroll") for (int n = 0; n < 2; ++n) _Pragma("unroll") for (int k = 0; k < 2; ++k) \
;         acc[ai][bj][m][n] = __builtin_amdgcn_mfma_f32_16x16x32_bf16(Bt[n][k], At[m][k], acc[ai][bj][m][n], 0, 0, 0); __builtin_amdgcn_s_setprio(0); } while (0)
; #define PG8_WAIT_V(n) asm volatile("s_waitcnt vmcnt(" #n ")" ::: "memory")
; #define PG8_WAIT_L(n) asm volatile("s_waitcnt lgkmcnt(" #n ")" ::: "memory")
; #define PG8_BAR __builtin_amdgcn_s_barrier()
; #define PG8_SCHED __builtin_amdgcn_sched_barrier(0)
; template <class Epi>
; __device__ __forceinline__ void gemm_phase(LAS unsigned char* lds, const Sched& S, const Epi& E) {
;     ...
;             const bool last = (t == nt - 2);
;             const char* a1 = cA + (size_t)(t + 1) * kstep;
;             const char* a2 = last ? nA : cA + (size_t)(t + 2) * kstep; const char* b2 = last ? nB : cB + (size_t)(t + 2) * kstep;
;             const char* a3 = a2 + kstep; const char* b3 = b2 + kstep;
;             PG8_LDB(B0, 0, 0); PG8_LDB(B1, 0, 1); PG8_SCHED; PG8_LDA(At, 0, 0); PG8_STAGE(PG8_SA(1, 1), a1 + hstepA, voffA);
;             PG8_WAIT_V(8); PG8_WAIT_L(0); PG8_BAR; PG8_MMA(0, 0, At, B0); PG8_MMA(0, 1, At, B1); PG8_BAR; PG8_SCHED;
;             PG8_LDA(At, 0, 1); PG8_STAGE(PG8_SB(0, 0), b2, voffB); PG8_STAGE(PG8_SB(0, 1), b2 + hstepB, voffB); PG8_STAGE(PG8_SA(0, 0), a2, voffA);
.LBB0_2100:
	s_add_u32 s28, s26, 0xfff80080
	s_addc_u32 s29, s27, -1
	s_add_i32 s49, 0, 0x10000
	s_cmp_eq_u32 s37, 4
	s_cselect_b32 s31, s5, s29
	s_cselect_b32 s30, s15, s28
	s_cselect_b32 s29, s17, s36
	s_cselect_b32 s28, s34, s35
	s_add_i32 s88, 0, 0x14000
	v_add_u32_e32 v106, s49, v197
	v_add_u32_e32 v158, s88, v197
	ds_read_b128 v[90:93], v106
	ds_read_b128 v[94:97], v106 offset:1024
	ds_read_b128 v[102:105], v106 offset:2048
	ds_read_b128 v[106:109], v106 offset:3072
	ds_read_b128 v[146:149], v158
	ds_read_b128 v[150:153], v158 offset:1024
	ds_read_b128 v[154:157], v158 offset:2048
	ds_read_b128 v[158:161], v158 offset:3072
	v_lshl_add_u64 v[200:201], s[26:27], 0, v[184:185]
	s_add_i32 m0, s64, 0xc000
	ds_read_b128 v[188:191], v199
	ds_read_b128 v[192:195], v199 offset:1024
	ds_read_b128 v[222:225], v199 offset:2048
	ds_read_b128 v[226:229], v199 offset:3072
	ds_read_b128 v[230:233], v199 offset:4096
	ds_read_b128 v[234:237], v199 offset:5120
	ds_read_b128 v[238:241], v199 offset:6144
	ds_read_b128 v[242:245], v199 offset:7168
	global_load_lds_dwordx4 v[200:201], off
	v_lshl_add_u64 v[200:201], s[26:27], 0, v[186:187]
	s_add_i32 m0, s64, 0xe000
	s_nop 0
	global_load_lds_dwordx4 v[200:201], off
	s_waitcnt vmcnt(8)
	s_waitcnt lgkmcnt(0)
	s_barrier
	s_setprio 1
	s_waitcnt lgkmcnt(0)
	v_mfma_f32_16x16x32_bf16 v[142:145], v[90:93], v[188:191], v[142:145]
	v_mfma_f32_16x16x32_bf16 v[138:141], v[102:105], v[188:191], v[138:141]
	v_mfma_f32_16x16x32_bf16 v[126:129], v[90:93], v[222:225], v[126:129]
	v_mfma_f32_16x16x32_bf16 v[122:125], v[102:105], v[222:225], v[122:125]
	v_mfma_f32_16x16x32_bf16 v[110:113], v[90:93], v[230:233], v[110:113]
	v_mfma_f32_16x16x32_bf16 v[98:101], v[102:105], v[230:233], v[98:101]
	v_mfma_f32_16x16x32_bf16 v[78:81], v[90:93], v[238:241], v[78:81]
	v_mfma_f32_16x16x32_bf16 v[74:77], v[102:105], v[238:241], v[74:77]
	v_mfma_f32_16x16x32_bf16 v[142:145], v[94:97], v[192:195], v[142:145]
	v_mfma_f32_16x16x32_bf16 v[138:141], v[106:109], v[192:195], v[138:141]
	v_mfma_f32_16x16x32_bf16 v[126:129], v[94:97], v[226:229], v[126:129]
	v_mfma_f32_16x16x32_bf16 v[122:125], v[106:109], v[226:229], v[122:125]
	v_mfma_f32_16x16x32_bf16 v[110:113], v[94:97], v[234:237], v[110:113]
	v_mfma_f32_16x16x32_bf16 v[98:101], v[106:109], v[234:237], v[98:101]
	v_mfma_f32_16x16x32_bf16 v[78:81], v[94:97], v[242:245], v[78:81]
	v_mfma_f32_16x16x32_bf16 v[74:77], v[106:109], v[242:245], v[74:77]
	s_setprio 0
	s_setprio 1
	v_mfma_f32_16x16x32_bf16 v[134:137], v[146:149], v[188:191], v[134:137]
	v_mfma_f32_16x16x32_bf16 v[130:133], v[154:157], v[188:191], v[130:133]
	v_mfma_f32_16x16x32_bf16 v[118:121], v[146:149], v[222:225], v[118:121]
	v_mfma_f32_16x16x32_bf16 v[114:117], v[154:157], v[222:225], v[114:117]
	v_mfma_f32_16x16x32_bf16 v[86:89], v[146:149], v[230:233], v[86:89]
	v_mfma_f32_16x16x32_bf16 v[82:85], v[154:157], v[230:233], v[82:85]
	v_mfma_f32_16x16x32_bf16 v[70:73], v[146:149], v[238:241], v[70:73]
	v_mfma_f32_16x16x32_bf16 v[66:69], v[154:157], v[238:241], v[66:69]
	v_mfma_f32_16x16x32_bf16 v[134:137], v[150:153], v[192:195], v[134:137]
	v_mfma_f32_16x16x32_bf16 v[130:133], v[158:161], v[192:195], v[130:133]
	v_mfma_f32_16x16x32_bf16 v[118:121], v[150:153], v[226:229], v[118:121]
	v_mfma_f32_16x16x32_bf16 v[114:117], v[158:161], v[226:229], v[114:117]
	s_setprio 2
	s_barrier
	v_mfma_f32_16x16x32_bf16 v[86:89], v[150:153], v[234:237], v[86:89]
	v_mfma_f32_16x16x32_bf16 v[82:85], v[158:161], v[234:237], v[82:85]
	v_mfma_f32_16x16x32_bf16 v[70:73], v[150:153], v[242:245], v[70:73]
	v_mfma_f32_16x16x32_bf16 v[66:69], v[158:161], v[242:245], v[66:69]
	s_setprio 0
	s_add_i32 s49, s49, s25
	v_lshl_add_u64 v[200:201], s[28:29], 0, v[168:169]
	s_mov_b32 m0, s49
	ds_read_b128 v[188:191], v199 offset:16384
	ds_read_b128 v[192:195], v199 offset:17408
	ds_read_b128 v[222:225], v199 offset:18432
	ds_read_b128 v[226:229], v199 offset:19456
	ds_read_b128 v[230:233], v199 offset:20480
	ds_read_b128 v[234:237], v199 offset:21504
	ds_read_b128 v[238:241], v199 offset:22528
	ds_read_b128 v[242:245], v199 offset:23552
	global_load_lds_dwordx4 v[200:201], off
	s_add_i32 m0, s49, 0x2000
	s_add_u32 s96, s28, 0x20000
	v_lshl_add_u64 v[246:247], s[28:29], 0, v[166:167]
	s_addc_u32 s97, s29, 0
	s_add_i32 s49, s88, s25
	global_load_lds_dwordx4 v[246:247], off
	v_lshl_add_u64 v[248:249], s[96:97], 0, v[168:169]
	s_mov_b32 m0, s49
	v_lshl_add_u64 v[250:251], s[30:31], 0, v[164:165]
	global_load_lds_dwordx4 v[248:249], off
	v_lshl_add_u64 v[248:249], s[96:97], 0, v[166:167]
	s_add_i32 m0, s49, 0x2000
	s_nop 0
	global_load_lds_dwordx4 v[248:249], off
	v_lshl_add_u64 v[248:249], s[30:31], 0, v[162:163]
	s_mov_b32 m0, s64
	s_nop 0
	global_load_lds_dwordx4 v[248:249], off
	s_mov_b32 m0, s65
	s_nop 0
	global_load_lds_dwordx4 v[250:251], off
	s_waitcnt vmcnt(8)
	s_waitcnt lgkmcnt(0)
	s_barrier
; #define PG8_STAGE(bufoff, gbase, voff) do { _Pragma("unroll") for (int _i = 0; _i < 2; ++_i) \
;         __builtin_amdgcn_global_load_lds((const unsigned*)((const char*)(gbase) + (voff)[_i]), (LAS unsigned*)(lds + (bufoff) + ldsw + _i * 8192), 16, 0, 0); } while (0)
; #define PG8_LDA(dst, b, h) do { _Pragma("unroll") for (int m = 0; m < 4; ++m) _Pragma("unroll") for (int k = 0; k < 2; ++k) dst[m][k] = *(const LAS bf16x8*)(lds + PG8_SA(b, h) + aoff + m * 2048 + k * 1024); } while (0)
; #define PG8_LDB(dst, b, h) do { _Pragma("unroll") for (int n = 0; n < 2; ++n) _Pragma("unroll") for (int k = 0; k < 2; ++k) dst[n][k] = *(const LAS bf16x8*)(lds + PG8_SB(b, h) + boff + n * 2048 + k * 1024); } while (0)
; #define PG8_MMA(ai, bj, At, Bt) do { __builtin_amdgcn_s_setprio(1); _Pragma("unroll") for (int m = 0; m < 4; ++m) _Pragma("unroll") for (int n = 0; n < 2; ++n) _Pragma("unroll") for (int k = 0; k < 2; ++k) \
;         acc[ai][bj][m][n] = __builtin_amdgcn_mfma_f32_16x16x32_bf16(Bt[n][k], At[m][k], acc[ai][bj][m][n], 0, 0, 0); __builtin_amdgcn_s_setprio(0); } while (0)
; #define PG8_WAIT_V(n) asm volatile("s_waitcnt vmcnt(" #n ")" ::: "memory")
; #define PG8_WAIT_L(n) asm volatile("s_waitcnt lgkmcnt(" #n ")" ::: "memory")
; #define PG8_BAR __builtin_amdgcn_s_barrier()
; #define PG8_SCHED __builtin_amdgcn_sched_barrier(0)
; template <class Epi>
; __device__ __forceinline__ void gemm_phase(LAS unsigned char* lds, const Sched& S, const Epi& E) {
;     ...
;             PG8_WAIT_V(8); PG8_WAIT_L(0); PG8_BAR; PG8_MMA(1, 0, At, B0); PG8_MMA(1, 1, At, B1); PG8_BAR; PG8_SCHED;
;             PG8_LDB(B0, 1, 0); PG8_LDB(B1, 1, 1); PG8_SCHED; PG8_LDA(At, 1, 0); PG8_STAGE(PG8_SA(0, 1), a2 + hstepA, voffA);
;             PG8_WAIT_V(8); PG8_WAIT_L(0); PG8_BAR; PG8_MMA(0, 0, At, B0); PG8_MMA(0, 1, At, B1); PG8_BAR; PG8_SCHED;
	s_setprio 1
	s_waitcnt lgkmcnt(0)
	v_mfma_f32_16x16x32_bf16 v[62:65], v[90:93], v[188:191], v[62:65]
	v_mfma_f32_16x16x32_bf16 v[58:61], v[102:105], v[188:191], v[58:61]
	v_mfma_f32_16x16x32_bf16 v[46:49], v[90:93], v[222:225], v[46:49]
	v_mfma_f32_16x16x32_bf16 v[42:45], v[102:105], v[222:225], v[42:45]
	v_mfma_f32_16x16x32_bf16 v[30:33], v[90:93], v[230:233], v[30:33]
	v_mfma_f32_16x16x32_bf16 v[26:29], v[102:105], v[230:233], v[26:29]
	v_mfma_f32_16x16x32_bf16 v[14:17], v[90:93], v[238:241], v[14:17]
	v_mfma_f32_16x16x32_bf16 v[10:13], v[102:105], v[238:241], v[10:13]
	v_mfma_f32_16x16x32_bf16 v[62:65], v[94:97], v[192:195], v[62:65]
	v_mfma_f32_16x16x32_bf16 v[58:61], v[106:109], v[192:195], v[58:61]
	v_mfma_f32_16x16x32_bf16 v[46:49], v[94:97], v[226:229], v[46:49]
	v_mfma_f32_16x16x32_bf16 v[42:45], v[106:109], v[226:229], v[42:45]
	v_mfma_f32_16x16x32_bf16 v[30:33], v[94:97], v[234:237], v[30:33]
	v_mfma_f32_16x16x32_bf16 v[26:29], v[106:109], v[234:237], v[26:29]
	v_mfma_f32_16x16x32_bf16 v[14:17], v[94:97], v[242:245], v[14:17]
	v_mfma_f32_16x16x32_bf16 v[10:13], v[106:109], v[242:245], v[10:13]
	s_setprio 0
	s_setprio 1
	v_mfma_f32_16x16x32_bf16 v[54:57], v[146:149], v[188:191], v[54:57]
	v_mfma_f32_16x16x32_bf16 v[50:53], v[154:157], v[188:191], v[50:53]
	v_mfma_f32_16x16x32_bf16 v[38:41], v[146:149], v[222:225], v[38:41]
	v_mfma_f32_16x16x32_bf16 v[34:37], v[154:157], v[222:225], v[34:37]
	v_mfma_f32_16x16x32_bf16 v[22:25], v[146:149], v[230:233], v[22:25]
	v_mfma_f32_16x16x32_bf16 v[18:21], v[154:157], v[230:233], v[18:21]
	v_mfma_f32_16x16x32_bf16 v[6:9], v[146:149], v[238:241], v[6:9]
	v_mfma_f32_16x16x32_bf16 v[2:5], v[154:157], v[238:241], v[2:5]
	v_mfma_f32_16x16x32_bf16 v[54:57], v[150:153], v[192:195], v[54:57]
	v_mfma_f32_16x16x32_bf16 v[50:53], v[158:161], v[192:195], v[50:53]
	v_mfma_f32_16x16x32_bf16 v[38:41], v[150:153], v[226:229], v[38:41]
	v_mfma_f32_16x16x32_bf16 v[34:37], v[158:161], v[226:229], v[34:37]
	s_setprio 2
	s_barrier
	v_mfma_f32_16x16x32_bf16 v[22:25], v[150:153], v[234:237], v[22:25]
	v_mfma_f32_16x16x32_bf16 v[18:21], v[158:161], v[234:237], v[18:21]
	v_mfma_f32_16x16x32_bf16 v[6:9], v[150:153], v[242:245], v[6:9]
	v_mfma_f32_16x16x32_bf16 v[2:5], v[158:161], v[242:245], v[2:5]
	s_setprio 0
	s_add_i32 s49, 0, 0x18000
	s_add_i32 s88, 0, 0x1c000
	v_add_u32_e32 v106, s49, v197
	v_add_u32_e32 v158, s88, v197
	ds_read_b128 v[90:93], v106
	ds_read_b128 v[94:97], v106 offset:1024
	ds_read_b128 v[102:105], v106 offset:2048
	ds_read_b128 v[106:109], v106 offset:3072
	ds_read_b128 v[146:149], v158
	ds_read_b128 v[150:153], v158 offset:1024
	ds_read_b128 v[154:157], v158 offset:2048
	ds_read_b128 v[158:161], v158 offset:3072
	s_add_u32 s30, s30, 0x80000
	s_addc_u32 s31, s31, 0
	s_mov_b32 m0, s66
	v_lshl_add_u64 v[252:253], s[30:31], 0, v[162:163]
	ds_read_b128 v[188:191], v199 offset:32768
	ds_read_b128 v[192:195], v199 offset:33792
	ds_read_b128 v[222:225], v199 offset:34816
	ds_read_b128 v[226:229], v199 offset:35840
	ds_read_b128 v[230:233], v199 offset:36864
	ds_read_b128 v[234:237], v199 offset:37888
	ds_read_b128 v[238:241], v199 offset:38912
	ds_read_b128 v[242:245], v199 offset:39936
	global_load_lds_dwordx4 v[252:253], off
	v_lshl_add_u64 v[252:253], s[30:31], 0, v[164:165]
	s_mov_b32 m0, s67
	s_nop 0
	global_load_lds_dwordx4 v[252:253], off
	s_waitcnt vmcnt(8)
	s_waitcnt lgkmcnt(0)
	s_barrier
	s_setprio 1
	s_waitcnt lgkmcnt(0)
	v_mfma_f32_16x16x32_bf16 v[142:145], v[90:93], v[188:191], v[142:145]
	v_mfma_f32_16x16x32_bf16 v[138:141], v[102:105], v[188:191], v[138:141]
	v_mfma_f32_16x16x32_bf16 v[126:129], v[90:93], v[222:225], v[126:129]
	v_mfma_f32_16x16x32_bf16 v[122:125], v[102:105], v[222:225], v[122:125]
	v_mfma_f32_16x16x32_bf16 v[110:113], v[90:93], v[230:233], v[110:113]
	v_mfma_f32_16x16x32_bf16 v[98:101], v[102:105], v[230:233], v[98:101]
	v_mfma_f32_16x16x32_bf16 v[78:81], v[90:93], v[238:241], v[78:81]
	v_mfma_f32_16x16x32_bf16 v[74:77], v[102:105], v[238:241], v[74:77]
	v_mfma_f32_16x16x32_bf16 v[142:145], v[94:97], v[192:195], v[142:145]
	v_mfma_f32_16x16x32_bf16 v[138:141], v[106:109], v[192:195], v[138:141]
	v_mfma_f32_16x16x32_bf16 v[126:129], v[94:97], v[226:229], v[126:129]
	v_mfma_f32_16x16x32_bf16 v[122:125], v[106:109], v[226:229], v[122:125]
	v_mfma_f32_16x16x32_bf16 v[110:113], v[94:97], v[234:237], v[110:113]
	v_mfma_f32_16x16x32_bf16 v[98:101], v[106:109], v[234:237], v[98:101]
	v_mfma_f32_16x16x32_bf16 v[78:81], v[94:97], v[242:245], v[78:81]
	v_mfma_f32_16x16x32_bf16 v[74:77], v[106:109], v[242:245], v[74:77]
	s_setprio 0
	s_setprio 1
	v_mfma_f32_16x16x32_bf16 v[134:137], v[146:149], v[188:191], v[134:137]
	v_mfma_f32_16x16x32_bf16 v[130:133], v[154:157], v[188:191], v[130:133]
	v_mfma_f32_16x16x32_bf16 v[118:121], v[146:149], v[222:225], v[118:121]
	v_mfma_f32_16x16x32_bf16 v[114:117], v[154:157], v[222:225], v[114:117]
	v_mfma_f32_16x16x32_bf16 v[86:89], v[146:149], v[230:233], v[86:89]
	v_mfma_f32_16x16x32_bf16 v[82:85], v[154:157], v[230:233], v[82:85]
	v_mfma_f32_16x16x32_bf16 v[70:73], v[146:149], v[238:241], v[70:73]
	v_mfma_f32_16x16x32_bf16 v[66:69], v[154:157], v[238:241], v[66:69]
	v_mfma_f32_16x16x32_bf16 v[134:137], v[150:153], v[192:195], v[134:137]
	v_mfma_f32_16x16x32_bf16 v[130:133], v[158:161], v[192:195], v[130:133]
	v_mfma_f32_16x16x32_bf16 v[118:121], v[150:153], v[226:229], v[118:121]
	v_mfma_f32_16x16x32_bf16 v[114:117], v[158:161], v[226:229], v[114:117]
	s_setprio 2
	s_barrier
; #define PG8_STAGE(bufoff, gbase, voff) do { _Pragma("unroll") for (int _i = 0; _i < 2; ++_i) \
;         __builtin_amdgcn_global_load_lds((const unsigned*)((const char*)(gbase) + (voff)[_i]), (LAS unsigned*)(lds + (bufoff) + ldsw + _i * 8192), 16, 0, 0); } while (0)
; #define PG8_LDA(dst, b, h) do { _Pragma("unroll") for (int m = 0; m < 4; ++m) _Pragma("unroll") for (int k = 0; k < 2; ++k) dst[m][k] = *(const LAS bf16x8*)(lds + PG8_SA(b, h) + aoff + m * 2048 + k * 1024); } while (0)
; #define PG8_MMA(ai, bj, At, Bt) do { __builtin_amdgcn_s_setprio(1); _Pragma("unroll") for (int m = 0; m < 4; ++m) _Pragma("unroll") for (int n = 0; n < 2; ++n) _Pragma("unroll") for (int k = 0; k < 2; ++k) \
;         acc[ai][bj][m][n] = __builtin_amdgcn_mfma_f32_16x16x32_bf16(Bt[n][k], At[m][k], acc[ai][bj][m][n], 0, 0, 0); __builtin_amdgcn_s_setprio(0); } while (0)
; #define PG8_WAIT_V(n) asm volatile("s_waitcnt vmcnt(" #n ")" ::: "memory")
; #define PG8_WAIT_L(n) asm volatile("s_waitcnt lgkmcnt(" #n ")" ::: "memory")
; #define PG8_BAR __builtin_amdgcn_s_barrier()
; #define PG8_SCHED __builtin_amdgcn_sched_barrier(0)
; template <class Epi>
; __device__ __forceinline__ void gemm_phase(LAS unsigned char* lds, const Sched& S, const Epi& E) {
;     ...
;             PG8_WAIT_V(8); PG8_WAIT_L(0); PG8_BAR; PG8_MMA(0, 0, At, B0); PG8_MMA(0, 1, At, B1); PG8_BAR; PG8_SCHED;
;             PG8_LDA(At, 1, 1); PG8_STAGE(PG8_SB(1, 0), b3, voffB); PG8_STAGE(PG8_SB(1, 1), b3 + hstepB, voffB); PG8_STAGE(PG8_SA(1, 0), a3, voffA);
;             PG8_WAIT_V(8); PG8_WAIT_L(0); PG8_BAR; PG8_MMA(1, 0, At, B0); PG8_MMA(1, 1, At, B1); PG8_BAR; PG8_SCHED;
;         }
;         if (wr == 0) PG8_BAR;
	v_mfma_f32_16x16x32_bf16 v[86:89], v[150:153], v[234:237], v[86:89]
	v_mfma_f32_16x16x32_bf16 v[82:85], v[158:161], v[234:237], v[82:85]
	v_mfma_f32_16x16x32_bf16 v[70:73], v[150:153], v[242:245], v[70:73]
	v_mfma_f32_16x16x32_bf16 v[66:69], v[158:161], v[242:245], v[66:69]
	s_setprio 0
	s_add_i32 s30, s49, s25
	v_lshl_add_u64 v[200:201], v[200:201], 0, s[0:1]
	s_mov_b32 m0, s30
	ds_read_b128 v[188:191], v199 offset:49152
	ds_read_b128 v[192:195], v199 offset:50176
	ds_read_b128 v[222:225], v199 offset:51200
	ds_read_b128 v[226:229], v199 offset:52224
	ds_read_b128 v[230:233], v199 offset:53248
	ds_read_b128 v[234:237], v199 offset:54272
	ds_read_b128 v[238:241], v199 offset:55296
	ds_read_b128 v[242:245], v199 offset:56320
	global_load_lds_dwordx4 v[200:201], off
	s_add_i32 m0, s30, 0x2000
	s_add_u32 s28, s28, 0x20080
	v_lshl_add_u64 v[200:201], v[246:247], 0, s[0:1]
	s_addc_u32 s29, s29, 0
	s_add_i32 s30, s88, s25
	global_load_lds_dwordx4 v[200:201], off
	v_lshl_add_u64 v[200:201], s[28:29], 0, v[168:169]
	s_mov_b32 m0, s30
	s_nop 0
	global_load_lds_dwordx4 v[200:201], off
	v_lshl_add_u64 v[200:201], s[28:29], 0, v[166:167]
	s_add_i32 m0, s30, 0x2000
	s_nop 0
	global_load_lds_dwordx4 v[200:201], off
	v_lshl_add_u64 v[200:201], v[248:249], 0, s[0:1]
	s_mov_b32 m0, s68
	s_nop 0
	global_load_lds_dwordx4 v[200:201], off
	v_lshl_add_u64 v[200:201], v[250:251], 0, s[0:1]
	s_mov_b32 m0, s69
	s_nop 0
	global_load_lds_dwordx4 v[200:201], off
	s_waitcnt vmcnt(8)
	s_waitcnt lgkmcnt(0)
	s_barrier
	s_setprio 1
	s_waitcnt lgkmcnt(0)
	v_mfma_f32_16x16x32_bf16 v[62:65], v[90:93], v[188:191], v[62:65]
	v_mfma_f32_16x16x32_bf16 v[58:61], v[102:105], v[188:191], v[58:61]
	v_mfma_f32_16x16x32_bf16 v[46:49], v[90:93], v[222:225], v[46:49]
	v_mfma_f32_16x16x32_bf16 v[42:45], v[102:105], v[222:225], v[42:45]
	v_mfma_f32_16x16x32_bf16 v[30:33], v[90:93], v[230:233], v[30:33]
	v_mfma_f32_16x16x32_bf16 v[26:29], v[102:105], v[230:233], v[26:29]
	v_mfma_f32_16x16x32_bf16 v[14:17], v[90:93], v[238:241], v[14:17]
	v_mfma_f32_16x16x32_bf16 v[10:13], v[102:105], v[238:241], v[10:13]
	v_mfma_f32_16x16x32_bf16 v[62:65], v[94:97], v[192:195], v[62:65]
	v_mfma_f32_16x16x32_bf16 v[58:61], v[106:109], v[192:195], v[58:61]
	v_mfma_f32_16x16x32_bf16 v[46:49], v[94:97], v[226:229], v[46:49]
	v_mfma_f32_16x16x32_bf16 v[42:45], v[106:109], v[226:229], v[42:45]
	v_mfma_f32_16x16x32_bf16 v[30:33], v[94:97], v[234:237], v[30:33]
	v_mfma_f32_16x16x32_bf16 v[26:29], v[106:109], v[234:237], v[26:29]
	v_mfma_f32_16x16x32_bf16 v[14:17], v[94:97], v[242:245], v[14:17]
	v_mfma_f32_16x16x32_bf16 v[10:13], v[106:109], v[242:245], v[10:13]
	s_setprio 0
	s_setprio 1
	v_mfma_f32_16x16x32_bf16 v[54:57], v[146:149], v[188:191], v[54:57]
	v_mfma_f32_16x16x32_bf16 v[50:53], v[154:157], v[188:191], v[50:53]
	v_mfma_f32_16x16x32_bf16 v[38:41], v[146:149], v[222:225], v[38:41]
	v_mfma_f32_16x16x32_bf16 v[34:37], v[154:157], v[222:225], v[34:37]
	v_mfma_f32_16x16x32_bf16 v[22:25], v[146:149], v[230:233], v[22:25]
	v_mfma_f32_16x16x32_bf16 v[18:21], v[154:157], v[230:233], v[18:21]
	v_mfma_f32_16x16x32_bf16 v[6:9], v[146:149], v[238:241], v[6:9]
	v_mfma_f32_16x16x32_bf16 v[2:5], v[154:157], v[238:241], v[2:5]
	v_mfma_f32_16x16x32_bf16 v[54:57], v[150:153], v[192:195], v[54:57]
	v_mfma_f32_16x16x32_bf16 v[50:53], v[158:161], v[192:195], v[50:53]
	v_mfma_f32_16x16x32_bf16 v[38:41], v[150:153], v[226:229], v[38:41]
	v_mfma_f32_16x16x32_bf16 v[34:37], v[158:161], v[226:229], v[34:37]
	s_setprio 2
	s_barrier
	v_mfma_f32_16x16x32_bf16 v[22:25], v[150:153], v[234:237], v[22:25]
	v_mfma_f32_16x16x32_bf16 v[18:21], v[158:161], v[234:237], v[18:21]
	v_mfma_f32_16x16x32_bf16 v[6:9], v[150:153], v[242:245], v[6:9]
	v_mfma_f32_16x16x32_bf16 v[2:5], v[158:161], v[242:245], v[2:5]
	s_setprio 0
	s_add_i32 s37, s37, 2
	s_add_u32 s26, s26, 0x100
	s_addc_u32 s27, s27, 0
	s_add_u32 s35, s35, 0x100
	s_addc_u32 s36, s36, 0
	s_cmp_gt_u32 s37, 5
	s_cbranch_scc0 .LBB0_2100
	s_and_b64 vcc, exec, s[12:13]
	s_cbranch_vccz .LBB0_2103
	s_barrier

; #define PG8_STAGE(bufoff, gbase, voff) do { _Pragma("unroll") for (int _i = 0; _i < 2; ++_i) \
;         __builtin_amdgcn_global_load_lds((const unsigned*)((const char*)(gbase) + (voff)[_i]), (LAS unsigned*)(lds + (bufoff) + ldsw + _i * 8192), 16, 0, 0); } while (0)
; #define PG8_LDA(dst, b, h) do { _Pragma("unroll") for (int m = 0; m < 4; ++m) _Pragma("unroll") for (int k = 0; k < 2; ++k) dst[m][k] = *(const LAS bf16x8*)(lds + PG8_SA(b, h) + aoff + m * 2048 + k * 1024); } while (0)
; #define PG8_LDB(dst, b, h) do { _Pragma("unroll") for (int n = 0; n < 2; ++n) _Pragma("unroll") for (int k = 0; k < 2; ++k) dst[n][k] = *(const LAS bf16x8*)(lds + PG8_SB(b, h) + boff + n * 2048 + k * 1024); } while (0)
; #define PG8_MMA(ai, bj, At, Bt) do { __builtin_amdgcn_s_setprio(1); _Pragma("unroll") for (int m = 0; m < 4; ++m) _Pragma("unroll") for (int n = 0; n < 2; ++n) _Pragma("unroll") for (int k = 0; k < 2; ++k) \
;         acc[ai][bj][m][n] = __builtin_amdgcn_mfma_f32_16x16x32_bf16(Bt[n][k], At[m][k], acc[ai][bj][m][n], 0, 0, 0); __builtin_amdgcn_s_setprio(0); } while (0)
; #define PG8_WAIT_V(n) asm volatile("s_waitcnt vmcnt(" #n ")" ::: "memory")
; #define PG8_WAIT_L(n) asm volatile("s_waitcnt lgkmcnt(" #n ")" ::: "memory")
; #define PG8_BAR __builtin_amdgcn_s_barrier()
; #define PG8_SCHED __builtin_amdgcn_sched_barrier(0)
; template <class Epi>
; __device__ __forceinline__ void gemm_phase(LAS unsigned char* lds, const Sched& S, const Epi& E) {
;     ...
;             const bool last = (t == nt - 2);
;             const char* a1 = cA + (size_t)(t + 1) * kstep;
;             const char* a2 = last ? nA : cA + (size_t)(t + 2) * kstep; const char* b2 = last ? nB : cB + (size_t)(t + 2) * kstep;
;             const char* a3 = a2 + kstep; const char* b3 = b2 + kstep;
;             PG8_LDB(B0, 0, 0); PG8_LDB(B1, 0, 1); PG8_SCHED; PG8_LDA(At, 0, 0); PG8_STAGE(PG8_SA(1, 1), a1 + hstepA, voffA);
;             PG8_WAIT_V(8); PG8_WAIT_L(0); PG8_BAR; PG8_MMA(0, 0, At, B0); PG8_MMA(0, 1, At, B1); PG8_BAR; PG8_SCHED;
;             PG8_LDA(At, 0, 1); PG8_STAGE(PG8_SB(0, 0), b2, voffB); PG8_STAGE(PG8_SB(0, 1), b2 + hstepB, voffB); PG8_STAGE(PG8_SA(0, 0), a2, voffA);
.LBB0_2278:
	s_add_u32 s26, s24, 0xfff80080
	s_addc_u32 s27, s25, -1
	s_add_i32 s49, 0, 0x10000
	s_cmp_eq_u32 s69, 28
	s_cselect_b32 s29, s19, s27
	s_cselect_b32 s28, s18, s26
	v_add_u32_e32 v157, s49, v153
	s_cselect_b32 s27, s23, s11
	s_cselect_b32 s26, s22, s9
	s_add_i32 s82, 0, 0x14000
	ds_read_b128 v[140:143], v157
	ds_read_b128 v[144:147], v157 offset:1024
	ds_read_b128 v[148:151], v157 offset:2048
	ds_read_b128 v[158:161], v157 offset:3072
	v_add_u32_e32 v157, s82, v153
	ds_read_b128 v[162:165], v157
	ds_read_b128 v[176:179], v157 offset:1024
	ds_read_b128 v[180:183], v157 offset:2048
	ds_read_b128 v[184:187], v157 offset:3072
	v_lshl_add_u64 v[166:167], s[24:25], 0, v[136:137]
	s_add_i32 m0, s38, 0xc000
	ds_read_b128 v[188:191], v156
	ds_read_b128 v[192:195], v156 offset:1024
	ds_read_b128 v[196:199], v156 offset:2048
	ds_read_b128 v[222:225], v156 offset:3072
	ds_read_b128 v[226:229], v156 offset:4096
	ds_read_b128 v[230:233], v156 offset:5120
	ds_read_b128 v[234:237], v156 offset:6144
	ds_read_b128 v[238:241], v156 offset:7168
	global_load_lds_dwordx4 v[166:167], off
	v_lshl_add_u64 v[166:167], s[24:25], 0, v[138:139]
	s_add_i32 m0, s38, 0xe000
	s_nop 0
	global_load_lds_dwordx4 v[166:167], off
	s_waitcnt vmcnt(8)
	s_waitcnt lgkmcnt(0)
	s_barrier
	s_setprio 1
	s_waitcnt lgkmcnt(0)
	v_mfma_f32_16x16x32_bf16 v[126:129], v[140:143], v[188:191], v[126:129]
	v_mfma_f32_16x16x32_bf16 v[118:121], v[148:151], v[188:191], v[118:121]
	v_mfma_f32_16x16x32_bf16 v[110:113], v[140:143], v[196:199], v[110:113]
	v_mfma_f32_16x16x32_bf16 v[102:105], v[148:151], v[196:199], v[102:105]
	v_mfma_f32_16x16x32_bf16 v[94:97], v[140:143], v[226:229], v[94:97]
	v_mfma_f32_16x16x32_bf16 v[86:89], v[148:151], v[226:229], v[86:89]
	v_mfma_f32_16x16x32_bf16 v[78:81], v[140:143], v[234:237], v[78:81]
	v_mfma_f32_16x16x32_bf16 v[70:73], v[148:151], v[234:237], v[70:73]
	v_mfma_f32_16x16x32_bf16 v[126:129], v[144:147], v[192:195], v[126:129]
	v_mfma_f32_16x16x32_bf16 v[118:121], v[158:161], v[192:195], v[118:121]
	v_mfma_f32_16x16x32_bf16 v[110:113], v[144:147], v[222:225], v[110:113]
	v_mfma_f32_16x16x32_bf16 v[102:105], v[158:161], v[222:225], v[102:105]
	v_mfma_f32_16x16x32_bf16 v[94:97], v[144:147], v[230:233], v[94:97]
	v_mfma_f32_16x16x32_bf16 v[86:89], v[158:161], v[230:233], v[86:89]
	v_mfma_f32_16x16x32_bf16 v[78:81], v[144:147], v[238:241], v[78:81]
	v_mfma_f32_16x16x32_bf16 v[70:73], v[158:161], v[238:241], v[70:73]
	s_setprio 0
	s_setprio 1
	v_mfma_f32_16x16x32_bf16 v[122:125], v[162:165], v[188:191], v[122:125]
	v_mfma_f32_16x16x32_bf16 v[114:117], v[180:183], v[188:191], v[114:117]
	v_mfma_f32_16x16x32_bf16 v[106:109], v[162:165], v[196:199], v[106:109]
	v_mfma_f32_16x16x32_bf16 v[98:101], v[180:183], v[196:199], v[98:101]
	v_mfma_f32_16x16x32_bf16 v[90:93], v[162:165], v[226:229], v[90:93]
	v_mfma_f32_16x16x32_bf16 v[82:85], v[180:183], v[226:229], v[82:85]
	v_mfma_f32_16x16x32_bf16 v[74:77], v[162:165], v[234:237], v[74:77]
	v_mfma_f32_16x16x32_bf16 v[66:69], v[180:183], v[234:237], v[66:69]
	v_mfma_f32_16x16x32_bf16 v[122:125], v[176:179], v[192:195], v[122:125]
	v_mfma_f32_16x16x32_bf16 v[114:117], v[184:187], v[192:195], v[114:117]
	v_mfma_f32_16x16x32_bf16 v[106:109], v[176:179], v[222:225], v[106:109]
	v_mfma_f32_16x16x32_bf16 v[98:101], v[184:187], v[222:225], v[98:101]
	s_setprio 2
	s_barrier
	v_mfma_f32_16x16x32_bf16 v[90:93], v[176:179], v[230:233], v[90:93]
	v_mfma_f32_16x16x32_bf16 v[82:85], v[184:187], v[230:233], v[82:85]
	v_mfma_f32_16x16x32_bf16 v[74:77], v[176:179], v[238:241], v[74:77]
	v_mfma_f32_16x16x32_bf16 v[66:69], v[184:187], v[238:241], v[66:69]
	s_setprio 0
	s_add_i32 s49, s49, s37
	v_lshl_add_u64 v[166:167], s[26:27], 0, v[168:169]
	s_mov_b32 m0, s49
	ds_read_b128 v[188:191], v156 offset:16384
	ds_read_b128 v[192:195], v156 offset:17408
	ds_read_b128 v[196:199], v156 offset:18432
	ds_read_b128 v[222:225], v156 offset:19456
	ds_read_b128 v[226:229], v156 offset:20480
	ds_read_b128 v[230:233], v156 offset:21504
	ds_read_b128 v[234:237], v156 offset:22528
	ds_read_b128 v[238:241], v156 offset:23552
	global_load_lds_dwordx4 v[166:167], off
	s_add_i32 m0, s49, 0x2000
	s_add_u32 s94, s26, 0x80000
	v_lshl_add_u64 v[200:201], s[26:27], 0, v[134:135]
	s_addc_u32 s95, s27, 0
	s_add_i32 s49, s82, s37
	global_load_lds_dwordx4 v[200:201], off
	v_lshl_add_u64 v[242:243], s[94:95], 0, v[168:169]
	s_mov_b32 m0, s49
	v_lshl_add_u64 v[244:245], s[28:29], 0, v[132:133]
	global_load_lds_dwordx4 v[242:243], off
	v_lshl_add_u64 v[242:243], s[94:95], 0, v[134:135]
	s_add_i32 m0, s49, 0x2000
	s_nop 0
	global_load_lds_dwordx4 v[242:243], off
	v_lshl_add_u64 v[242:243], s[28:29], 0, v[130:131]
	s_mov_b32 m0, s38
	s_nop 0
	global_load_lds_dwordx4 v[242:243], off
	s_mov_b32 m0, s39
	s_nop 0
	global_load_lds_dwordx4 v[244:245], off
	s_waitcnt vmcnt(8)
	s_waitcnt lgkmcnt(0)
	s_barrier
; #define PG8_STAGE(bufoff, gbase, voff) do { _Pragma("unroll") for (int _i = 0; _i < 2; ++_i) \
;         __builtin_amdgcn_global_load_lds((const unsigned*)((const char*)(gbase) + (voff)[_i]), (LAS unsigned*)(lds + (bufoff) + ldsw + _i * 8192), 16, 0, 0); } while (0)
; #define PG8_LDA(dst, b, h) do { _Pragma("unroll") for (int m = 0; m < 4; ++m) _Pragma("unroll") for (int k = 0; k < 2; ++k) dst[m][k] = *(const LAS bf16x8*)(lds + PG8_SA(b, h) + aoff + m * 2048 + k * 1024); } while (0)
; #define PG8_LDB(dst, b, h) do { _Pragma("unroll") for (int n = 0; n < 2; ++n) _Pragma("unroll") for (int k = 0; k < 2; ++k) dst[n][k] = *(const LAS bf16x8*)(lds + PG8_SB(b, h) + boff + n * 2048 + k * 1024); } while (0)
; #define PG8_MMA(ai, bj, At, Bt) do { __builtin_amdgcn_s_setprio(1); _Pragma("unroll") for (int m = 0; m < 4; ++m) _Pragma("unroll") for (int n = 0; n < 2; ++n) _Pragma("unroll") for (int k = 0; k < 2; ++k) \
;         acc[ai][bj][m][n] = __builtin_amdgcn_mfma_f32_16x16x32_bf16(Bt[n][k], At[m][k], acc[ai][bj][m][n], 0, 0, 0); __builtin_amdgcn_s_setprio(0); } while (0)
; #define PG8_WAIT_V(n) asm volatile("s_waitcnt vmcnt(" #n ")" ::: "memory")
; #define PG8_WAIT_L(n) asm volatile("s_waitcnt lgkmcnt(" #n ")" ::: "memory")
; #define PG8_BAR __builtin_amdgcn_s_barrier()
; #define PG8_SCHED __builtin_amdgcn_sched_barrier(0)
; template <class Epi>
; __device__ __forceinline__ void gemm_phase(LAS unsigned char* lds, const Sched& S, const Epi& E) {
;     ...
;             PG8_WAIT_V(8); PG8_WAIT_L(0); PG8_BAR; PG8_MMA(1, 0, At, B0); PG8_MMA(1, 1, At, B1); PG8_BAR; PG8_SCHED;
;             PG8_LDB(B0, 1, 0); PG8_LDB(B1, 1, 1); PG8_SCHED; PG8_LDA(At, 1, 0); PG8_STAGE(PG8_SA(0, 1), a2 + hstepA, voffA);
;             PG8_WAIT_V(8); PG8_WAIT_L(0); PG8_BAR; PG8_MMA(0, 0, At, B0); PG8_MMA(0, 1, At, B1); PG8_BAR; PG8_SCHED;
	s_setprio 1
	s_waitcnt lgkmcnt(0)
	v_mfma_f32_16x16x32_bf16 v[62:65], v[140:143], v[188:191], v[62:65]
	v_mfma_f32_16x16x32_bf16 v[54:57], v[148:151], v[188:191], v[54:57]
	v_mfma_f32_16x16x32_bf16 v[46:49], v[140:143], v[196:199], v[46:49]
	v_mfma_f32_16x16x32_bf16 v[38:41], v[148:151], v[196:199], v[38:41]
	v_mfma_f32_16x16x32_bf16 v[30:33], v[140:143], v[226:229], v[30:33]
	v_mfma_f32_16x16x32_bf16 v[22:25], v[148:151], v[226:229], v[22:25]
	v_mfma_f32_16x16x32_bf16 v[14:17], v[140:143], v[234:237], v[14:17]
	v_mfma_f32_16x16x32_bf16 v[6:9], v[148:151], v[234:237], v[6:9]
	v_mfma_f32_16x16x32_bf16 v[62:65], v[144:147], v[192:195], v[62:65]
	v_mfma_f32_16x16x32_bf16 v[54:57], v[158:161], v[192:195], v[54:57]
	v_mfma_f32_16x16x32_bf16 v[46:49], v[144:147], v[222:225], v[46:49]
	v_mfma_f32_16x16x32_bf16 v[38:41], v[158:161], v[222:225], v[38:41]
	v_mfma_f32_16x16x32_bf16 v[30:33], v[144:147], v[230:233], v[30:33]
	v_mfma_f32_16x16x32_bf16 v[22:25], v[158:161], v[230:233], v[22:25]
	v_mfma_f32_16x16x32_bf16 v[14:17], v[144:147], v[238:241], v[14:17]
	v_mfma_f32_16x16x32_bf16 v[6:9], v[158:161], v[238:241], v[6:9]
	s_setprio 0
	s_setprio 1
	v_mfma_f32_16x16x32_bf16 v[58:61], v[162:165], v[188:191], v[58:61]
	v_mfma_f32_16x16x32_bf16 v[50:53], v[180:183], v[188:191], v[50:53]
	v_mfma_f32_16x16x32_bf16 v[42:45], v[162:165], v[196:199], v[42:45]
	v_mfma_f32_16x16x32_bf16 v[34:37], v[180:183], v[196:199], v[34:37]
	v_mfma_f32_16x16x32_bf16 v[26:29], v[162:165], v[226:229], v[26:29]
	v_mfma_f32_16x16x32_bf16 v[18:21], v[180:183], v[226:229], v[18:21]
	v_mfma_f32_16x16x32_bf16 v[10:13], v[162:165], v[234:237], v[10:13]
	v_mfma_f32_16x16x32_bf16 v[2:5], v[180:183], v[234:237], v[2:5]
	v_mfma_f32_16x16x32_bf16 v[58:61], v[176:179], v[192:195], v[58:61]
	v_mfma_f32_16x16x32_bf16 v[50:53], v[184:187], v[192:195], v[50:53]
	v_mfma_f32_16x16x32_bf16 v[42:45], v[176:179], v[222:225], v[42:45]
	v_mfma_f32_16x16x32_bf16 v[34:37], v[184:187], v[222:225], v[34:37]
	s_setprio 2
	s_barrier
	v_mfma_f32_16x16x32_bf16 v[26:29], v[176:179], v[230:233], v[26:29]
	v_mfma_f32_16x16x32_bf16 v[18:21], v[184:187], v[230:233], v[18:21]
	v_mfma_f32_16x16x32_bf16 v[10:13], v[176:179], v[238:241], v[10:13]
	v_mfma_f32_16x16x32_bf16 v[2:5], v[184:187], v[238:241], v[2:5]
	s_setprio 0
	s_add_i32 s49, 0, 0x18000
	v_add_u32_e32 v157, s49, v153
	s_add_i32 s82, 0, 0x1c000
	ds_read_b128 v[140:143], v157
	ds_read_b128 v[144:147], v157 offset:1024
	ds_read_b128 v[148:151], v157 offset:2048
	ds_read_b128 v[158:161], v157 offset:3072
	v_add_u32_e32 v157, s82, v153
	ds_read_b128 v[162:165], v157
	ds_read_b128 v[176:179], v157 offset:1024
	ds_read_b128 v[180:183], v157 offset:2048
	ds_read_b128 v[184:187], v157 offset:3072
	s_add_u32 s28, s28, 0x80000
	s_addc_u32 s29, s29, 0
	s_mov_b32 m0, s58
	v_lshl_add_u64 v[246:247], s[28:29], 0, v[130:131]
	ds_read_b128 v[188:191], v156 offset:32768
	ds_read_b128 v[192:195], v156 offset:33792
	ds_read_b128 v[196:199], v156 offset:34816
	ds_read_b128 v[222:225], v156 offset:35840
	ds_read_b128 v[226:229], v156 offset:36864
	ds_read_b128 v[230:233], v156 offset:37888
	ds_read_b128 v[234:237], v156 offset:38912
	ds_read_b128 v[238:241], v156 offset:39936
	global_load_lds_dwordx4 v[246:247], off
	v_lshl_add_u64 v[246:247], s[28:29], 0, v[132:133]
	s_mov_b32 m0, s59
	s_nop 0
	global_load_lds_dwordx4 v[246:247], off
	s_waitcnt vmcnt(8)
	s_waitcnt lgkmcnt(0)
	s_barrier
	s_setprio 1
	s_waitcnt lgkmcnt(0)
	v_mfma_f32_16x16x32_bf16 v[126:129], v[140:143], v[188:191], v[126:129]
	v_mfma_f32_16x16x32_bf16 v[118:121], v[148:151], v[188:191], v[118:121]
	v_mfma_f32_16x16x32_bf16 v[110:113], v[140:143], v[196:199], v[110:113]
	v_mfma_f32_16x16x32_bf16 v[102:105], v[148:151], v[196:199], v[102:105]
	v_mfma_f32_16x16x32_bf16 v[94:97], v[140:143], v[226:229], v[94:97]
	v_mfma_f32_16x16x32_bf16 v[86:89], v[148:151], v[226:229], v[86:89]
	v_mfma_f32_16x16x32_bf16 v[78:81], v[140:143], v[234:237], v[78:81]
	v_mfma_f32_16x16x32_bf16 v[70:73], v[148:151], v[234:237], v[70:73]
	v_mfma_f32_16x16x32_bf16 v[126:129], v[144:147], v[192:195], v[126:129]
	v_mfma_f32_16x16x32_bf16 v[118:121], v[158:161], v[192:195], v[118:121]
	v_mfma_f32_16x16x32_bf16 v[110:113], v[144:147], v[222:225], v[110:113]
	v_mfma_f32_16x16x32_bf16 v[102:105], v[158:161], v[222:225], v[102:105]
	v_mfma_f32_16x16x32_bf16 v[94:97], v[144:147], v[230:233], v[94:97]
	v_mfma_f32_16x16x32_bf16 v[86:89], v[158:161], v[230:233], v[86:89]
	v_mfma_f32_16x16x32_bf16 v[78:81], v[144:147], v[238:241], v[78:81]
	v_mfma_f32_16x16x32_bf16 v[70:73], v[158:161], v[238:241], v[70:73]
	s_setprio 0
	s_setprio 1
	v_mfma_f32_16x16x32_bf16 v[122:125], v[162:165], v[188:191], v[122:125]
	v_mfma_f32_16x16x32_bf16 v[114:117], v[180:183], v[188:191], v[114:117]
	v_mfma_f32_16x16x32_bf16 v[106:109], v[162:165], v[196:199], v[106:109]
	v_mfma_f32_16x16x32_bf16 v[98:101], v[180:183], v[196:199], v[98:101]
	v_mfma_f32_16x16x32_bf16 v[90:93], v[162:165], v[226:229], v[90:93]
	v_mfma_f32_16x16x32_bf16 v[82:85], v[180:183], v[226:229], v[82:85]
	v_mfma_f32_16x16x32_bf16 v[74:77], v[162:165], v[234:237], v[74:77]
	v_mfma_f32_16x16x32_bf16 v[66:69], v[180:183], v[234:237], v[66:69]
	v_mfma_f32_16x16x32_bf16 v[122:125], v[176:179], v[192:195], v[122:125]
	v_mfma_f32_16x16x32_bf16 v[114:117], v[184:187], v[192:195], v[114:117]
	v_mfma_f32_16x16x32_bf16 v[106:109], v[176:179], v[222:225], v[106:109]
	v_mfma_f32_16x16x32_bf16 v[98:101], v[184:187], v[222:225], v[98:101]
	s_setprio 2
	s_barrier
; #define PG8_STAGE(bufoff, gbase, voff) do { _Pragma("unroll") for (int _i = 0; _i < 2; ++_i) \
;         __builtin_amdgcn_global_load_lds((const unsigned*)((const char*)(gbase) + (voff)[_i]), (LAS unsigned*)(lds + (bufoff) + ldsw + _i * 8192), 16, 0, 0); } while (0)
; #define PG8_LDA(dst, b, h) do { _Pragma("unroll") for (int m = 0; m < 4; ++m) _Pragma("unroll") for (int k = 0; k < 2; ++k) dst[m][k] = *(const LAS bf16x8*)(lds + PG8_SA(b, h) + aoff + m * 2048 + k * 1024); } while (0)
; #define PG8_MMA(ai, bj, At, Bt) do { __builtin_amdgcn_s_setprio(1); _Pragma("unroll") for (int m = 0; m < 4; ++m) _Pragma("unroll") for (int n = 0; n < 2; ++n) _Pragma("unroll") for (int k = 0; k < 2; ++k) \
;         acc[ai][bj][m][n] = __builtin_amdgcn_mfma_f32_16x16x32_bf16(Bt[n][k], At[m][k], acc[ai][bj][m][n], 0, 0, 0); __builtin_amdgcn_s_setprio(0); } while (0)
; #define PG8_WAIT_V(n) asm volatile("s_waitcnt vmcnt(" #n ")" ::: "memory")
; #define PG8_WAIT_L(n) asm volatile("s_waitcnt lgkmcnt(" #n ")" ::: "memory")
; #define PG8_BAR __builtin_amdgcn_s_barrier()
; #define PG8_SCHED __builtin_amdgcn_sched_barrier(0)
; template <class Epi>
; __device__ __forceinline__ void gemm_phase(LAS unsigned char* lds, const Sched& S, const Epi& E) {
;     ...
;             PG8_WAIT_V(8); PG8_WAIT_L(0); PG8_BAR; PG8_MMA(0, 0, At, B0); PG8_MMA(0, 1, At, B1); PG8_BAR; PG8_SCHED;
;             PG8_LDA(At, 1, 1); PG8_STAGE(PG8_SB(1, 0), b3, voffB); PG8_STAGE(PG8_SB(1, 1), b3 + hstepB, voffB); PG8_STAGE(PG8_SA(1, 0), a3, voffA);
;             PG8_WAIT_V(8); PG8_WAIT_L(0); PG8_BAR; PG8_MMA(1, 0, At, B0); PG8_MMA(1, 1, At, B1); PG8_BAR; PG8_SCHED;
;         }
;         if (wr == 0) PG8_BAR;
	v_mfma_f32_16x16x32_bf16 v[90:93], v[176:179], v[230:233], v[90:93]
	v_mfma_f32_16x16x32_bf16 v[82:85], v[184:187], v[230:233], v[82:85]
	v_mfma_f32_16x16x32_bf16 v[74:77], v[176:179], v[238:241], v[74:77]
	v_mfma_f32_16x16x32_bf16 v[66:69], v[184:187], v[238:241], v[66:69]
	s_setprio 0
	s_add_i32 s28, s49, s37
	v_lshl_add_u64 v[166:167], v[166:167], 0, s[0:1]
	s_mov_b32 m0, s28
	ds_read_b128 v[188:191], v156 offset:49152
	ds_read_b128 v[192:195], v156 offset:50176
	ds_read_b128 v[196:199], v156 offset:51200
	ds_read_b128 v[222:225], v156 offset:52224
	ds_read_b128 v[226:229], v156 offset:53248
	ds_read_b128 v[230:233], v156 offset:54272
	ds_read_b128 v[234:237], v156 offset:55296
	ds_read_b128 v[238:241], v156 offset:56320
	global_load_lds_dwordx4 v[166:167], off
	s_add_i32 m0, s28, 0x2000
	s_add_u32 s26, s26, 0x80080
	v_lshl_add_u64 v[166:167], v[200:201], 0, s[0:1]
	s_addc_u32 s27, s27, 0
	s_add_i32 s28, s82, s37
	global_load_lds_dwordx4 v[166:167], off
	v_lshl_add_u64 v[166:167], s[26:27], 0, v[168:169]
	s_mov_b32 m0, s28
	s_nop 0
	global_load_lds_dwordx4 v[166:167], off
	v_lshl_add_u64 v[166:167], s[26:27], 0, v[134:135]
	s_add_i32 m0, s28, 0x2000
	s_nop 0
	global_load_lds_dwordx4 v[166:167], off
	v_lshl_add_u64 v[166:167], v[242:243], 0, s[0:1]
	s_mov_b32 m0, s64
	s_nop 0
	global_load_lds_dwordx4 v[166:167], off
	v_lshl_add_u64 v[166:167], v[244:245], 0, s[0:1]
	s_mov_b32 m0, s65
	s_nop 0
	global_load_lds_dwordx4 v[166:167], off
	s_waitcnt vmcnt(8)
	s_waitcnt lgkmcnt(0)
	s_barrier
	s_setprio 1
	s_waitcnt lgkmcnt(0)
	v_mfma_f32_16x16x32_bf16 v[62:65], v[140:143], v[188:191], v[62:65]
	v_mfma_f32_16x16x32_bf16 v[54:57], v[148:151], v[188:191], v[54:57]
	v_mfma_f32_16x16x32_bf16 v[46:49], v[140:143], v[196:199], v[46:49]
	v_mfma_f32_16x16x32_bf16 v[38:41], v[148:151], v[196:199], v[38:41]
	v_mfma_f32_16x16x32_bf16 v[30:33], v[140:143], v[226:229], v[30:33]
	v_mfma_f32_16x16x32_bf16 v[22:25], v[148:151], v[226:229], v[22:25]
	v_mfma_f32_16x16x32_bf16 v[14:17], v[140:143], v[234:237], v[14:17]
	v_mfma_f32_16x16x32_bf16 v[6:9], v[148:151], v[234:237], v[6:9]
	v_mfma_f32_16x16x32_bf16 v[62:65], v[144:147], v[192:195], v[62:65]
	v_mfma_f32_16x16x32_bf16 v[54:57], v[158:161], v[192:195], v[54:57]
	v_mfma_f32_16x16x32_bf16 v[46:49], v[144:147], v[222:225], v[46:49]
	v_mfma_f32_16x16x32_bf16 v[38:41], v[158:161], v[222:225], v[38:41]
	v_mfma_f32_16x16x32_bf16 v[30:33], v[144:147], v[230:233], v[30:33]
	v_mfma_f32_16x16x32_bf16 v[22:25], v[158:161], v[230:233], v[22:25]
	v_mfma_f32_16x16x32_bf16 v[14:17], v[144:147], v[238:241], v[14:17]
	v_mfma_f32_16x16x32_bf16 v[6:9], v[158:161], v[238:241], v[6:9]
	s_setprio 0
	s_setprio 1
	v_mfma_f32_16x16x32_bf16 v[58:61], v[162:165], v[188:191], v[58:61]
	v_mfma_f32_16x16x32_bf16 v[50:53], v[180:183], v[188:191], v[50:53]
	v_mfma_f32_16x16x32_bf16 v[42:45], v[162:165], v[196:199], v[42:45]
	v_mfma_f32_16x16x32_bf16 v[34:37], v[180:183], v[196:199], v[34:37]
	v_mfma_f32_16x16x32_bf16 v[26:29], v[162:165], v[226:229], v[26:29]
	v_mfma_f32_16x16x32_bf16 v[18:21], v[180:183], v[226:229], v[18:21]
	v_mfma_f32_16x16x32_bf16 v[10:13], v[162:165], v[234:237], v[10:13]
	v_mfma_f32_16x16x32_bf16 v[2:5], v[180:183], v[234:237], v[2:5]
	v_mfma_f32_16x16x32_bf16 v[58:61], v[176:179], v[192:195], v[58:61]
	v_mfma_f32_16x16x32_bf16 v[50:53], v[184:187], v[192:195], v[50:53]
	v_mfma_f32_16x16x32_bf16 v[42:45], v[176:179], v[222:225], v[42:45]
	v_mfma_f32_16x16x32_bf16 v[34:37], v[184:187], v[222:225], v[34:37]
	s_setprio 2
	s_barrier
	v_mfma_f32_16x16x32_bf16 v[26:29], v[176:179], v[230:233], v[26:29]
	v_mfma_f32_16x16x32_bf16 v[18:21], v[184:187], v[230:233], v[18:21]
	v_mfma_f32_16x16x32_bf16 v[10:13], v[176:179], v[238:241], v[10:13]
	v_mfma_f32_16x16x32_bf16 v[2:5], v[184:187], v[238:241], v[2:5]
	s_setprio 0
	s_add_i32 s69, s69, 2
	s_add_u32 s24, s24, 0x100
	s_addc_u32 s25, s25, 0
	s_add_u32 s9, s9, 0x100
	s_addc_u32 s11, s11, 0
	s_cmp_gt_u32 s69, 29
	s_cbranch_scc0 .LBB0_2278
	s_and_b64 vcc, exec, s[6:7]
	s_cbranch_vccz .LBB0_2281
	s_barrier

; #define PG8_STAGE(bufoff, gbase, voff) do { _Pragma("unroll") for (int _i = 0; _i < 2; ++_i) \
;         __builtin_amdgcn_global_load_lds((const unsigned*)((const char*)(gbase) + (voff)[_i]), (LAS unsigned*)(lds + (bufoff) + ldsw + _i * 8192), 16, 0, 0); } while (0)
; #define PG8_LDA(dst, b, h) do { _Pragma("unroll") for (int m = 0; m < 4; ++m) _Pragma("unroll") for (int k = 0; k < 2; ++k) dst[m][k] = *(const LAS bf16x8*)(lds + PG8_SA(b, h) + aoff + m * 2048 + k * 1024); } while (0)
; #define PG8_LDB(dst, b, h) do { _Pragma("unroll") for (int n = 0; n < 2; ++n) _Pragma("unroll") for (int k = 0; k < 2; ++k) dst[n][k] = *(const LAS bf16x8*)(lds + PG8_SB(b, h) + boff + n * 2048 + k * 1024); } while (0)
; #define PG8_MMA(ai, bj, At, Bt) do { __builtin_amdgcn_s_setprio(1); _Pragma("unroll") for (int m = 0; m < 4; ++m) _Pragma("unroll") for (int n = 0; n < 2; ++n) _Pragma("unroll") for (int k = 0; k < 2; ++k) \
;         acc[ai][bj][m][n] = __builtin_amdgcn_mfma_f32_16x16x32_bf16(Bt[n][k], At[m][k], acc[ai][bj][m][n], 0, 0, 0); __builtin_amdgcn_s_setprio(0); } while (0)
; #define PG8_WAIT_V(n) asm volatile("s_waitcnt vmcnt(" #n ")" ::: "memory")
; #define PG8_WAIT_L(n) asm volatile("s_waitcnt lgkmcnt(" #n ")" ::: "memory")
; #define PG8_BAR __builtin_amdgcn_s_barrier()
; #define PG8_SCHED __builtin_amdgcn_sched_barrier(0)
; template <class Epi>
; __device__ __forceinline__ void gemm_phase(LAS unsigned char* lds, const Sched& S, const Epi& E) {
;     ...
;             const bool last = (t == nt - 2);
;             const char* a1 = cA + (size_t)(t + 1) * kstep;
;             const char* a2 = last ? nA : cA + (size_t)(t + 2) * kstep; const char* b2 = last ? nB : cB + (size_t)(t + 2) * kstep;
;             const char* a3 = a2 + kstep; const char* b3 = b2 + kstep;
;             PG8_LDB(B0, 0, 0); PG8_LDB(B1, 0, 1); PG8_SCHED; PG8_LDA(At, 0, 0); PG8_STAGE(PG8_SA(1, 1), a1 + hstepA, voffA);
;             PG8_WAIT_V(8); PG8_WAIT_L(0); PG8_BAR; PG8_MMA(0, 0, At, B0); PG8_MMA(0, 1, At, B1); PG8_BAR; PG8_SCHED;
;             PG8_LDA(At, 0, 1); PG8_STAGE(PG8_SB(0, 0), b2, voffB); PG8_STAGE(PG8_SB(0, 1), b2 + hstepB, voffB); PG8_STAGE(PG8_SA(0, 0), a2, voffA);
.LBB0_2391:
	s_add_i32 s49, s22, 2
	s_add_u32 s23, s4, 0xffea0080
	s_addc_u32 s24, s5, -1
	s_add_i32 s88, 0, 0x10000
	s_cmp_eq_u32 s97, s22
	s_cselect_b32 s25, s26, s24
	s_cselect_b32 s24, s27, s23
	s_cselect_b32 s23, s95, vcc_hi
	s_cselect_b32 s22, s96, vcc_lo
	s_add_i32 s72, 0, 0x14000
	v_add_u32_e32 v142, s88, v222
	v_add_u32_e32 v158, s72, v222
	ds_read_b128 v[130:133], v142
	ds_read_b128 v[134:137], v142 offset:1024
	ds_read_b128 v[138:141], v142 offset:2048
	ds_read_b128 v[142:145], v142 offset:3072
	ds_read_b128 v[146:149], v158
	ds_read_b128 v[150:153], v158 offset:1024
	ds_read_b128 v[154:157], v158 offset:2048
	ds_read_b128 v[158:161], v158 offset:3072
	v_lshl_add_u64 v[166:167], s[4:5], 0, v[186:187]
	s_add_i32 m0, s35, 0xc000
	ds_read_b128 v[162:165], v224
	ds_read_b128 v[190:193], v224 offset:1024
	ds_read_b128 v[194:197], v224 offset:2048
	ds_read_b128 v[198:201], v224 offset:3072
	ds_read_b128 v[226:229], v224 offset:4096
	ds_read_b128 v[230:233], v224 offset:5120
	ds_read_b128 v[234:237], v224 offset:6144
	ds_read_b128 v[238:241], v224 offset:7168
	global_load_lds_dwordx4 v[166:167], off
	v_lshl_add_u64 v[166:167], s[4:5], 0, v[188:189]
	s_add_i32 m0, s35, 0xe000
	s_nop 0
	global_load_lds_dwordx4 v[166:167], off
	s_waitcnt vmcnt(8)
	s_waitcnt lgkmcnt(0)
	s_barrier
	s_setprio 1
	s_waitcnt lgkmcnt(0)
	v_mfma_f32_16x16x32_bf16 v[126:129], v[130:133], v[162:165], v[126:129]
	v_mfma_f32_16x16x32_bf16 v[122:125], v[138:141], v[162:165], v[122:125]
	v_mfma_f32_16x16x32_bf16 v[118:121], v[130:133], v[194:197], v[118:121]
	v_mfma_f32_16x16x32_bf16 v[106:109], v[138:141], v[194:197], v[106:109]
	v_mfma_f32_16x16x32_bf16 v[94:97], v[130:133], v[226:229], v[94:97]
	v_mfma_f32_16x16x32_bf16 v[90:93], v[138:141], v[226:229], v[90:93]
	v_mfma_f32_16x16x32_bf16 v[86:89], v[130:133], v[234:237], v[86:89]
	v_mfma_f32_16x16x32_bf16 v[74:77], v[138:141], v[234:237], v[74:77]
	v_mfma_f32_16x16x32_bf16 v[126:129], v[134:137], v[190:193], v[126:129]
	v_mfma_f32_16x16x32_bf16 v[122:125], v[142:145], v[190:193], v[122:125]
	v_mfma_f32_16x16x32_bf16 v[118:121], v[134:137], v[198:201], v[118:121]
	v_mfma_f32_16x16x32_bf16 v[106:109], v[142:145], v[198:201], v[106:109]
	v_mfma_f32_16x16x32_bf16 v[94:97], v[134:137], v[230:233], v[94:97]
	v_mfma_f32_16x16x32_bf16 v[90:93], v[142:145], v[230:233], v[90:93]
	v_mfma_f32_16x16x32_bf16 v[86:89], v[134:137], v[238:241], v[86:89]
	v_mfma_f32_16x16x32_bf16 v[74:77], v[142:145], v[238:241], v[74:77]
	s_setprio 0
	s_setprio 1
	v_mfma_f32_16x16x32_bf16 v[114:117], v[146:149], v[162:165], v[114:117]
	v_mfma_f32_16x16x32_bf16 v[110:113], v[154:157], v[162:165], v[110:113]
	v_mfma_f32_16x16x32_bf16 v[102:105], v[146:149], v[194:197], v[102:105]
	v_mfma_f32_16x16x32_bf16 v[98:101], v[154:157], v[194:197], v[98:101]
	v_mfma_f32_16x16x32_bf16 v[82:85], v[146:149], v[226:229], v[82:85]
	v_mfma_f32_16x16x32_bf16 v[78:81], v[154:157], v[226:229], v[78:81]
	v_mfma_f32_16x16x32_bf16 v[70:73], v[146:149], v[234:237], v[70:73]
	v_mfma_f32_16x16x32_bf16 v[66:69], v[154:157], v[234:237], v[66:69]
	v_mfma_f32_16x16x32_bf16 v[114:117], v[150:153], v[190:193], v[114:117]
	v_mfma_f32_16x16x32_bf16 v[110:113], v[158:161], v[190:193], v[110:113]
	v_mfma_f32_16x16x32_bf16 v[102:105], v[150:153], v[198:201], v[102:105]
	v_mfma_f32_16x16x32_bf16 v[98:101], v[158:161], v[198:201], v[98:101]
	s_setprio 2
	s_barrier
	v_mfma_f32_16x16x32_bf16 v[82:85], v[150:153], v[230:233], v[82:85]
	v_mfma_f32_16x16x32_bf16 v[78:81], v[158:161], v[230:233], v[78:81]
	v_mfma_f32_16x16x32_bf16 v[70:73], v[150:153], v[238:241], v[70:73]
	v_mfma_f32_16x16x32_bf16 v[66:69], v[158:161], v[238:241], v[66:69]
	s_setprio 0
	s_add_i32 s73, s88, s34
	v_lshl_add_u64 v[166:167], s[22:23], 0, v[168:169]
	s_mov_b32 m0, s73
	ds_read_b128 v[162:165], v224 offset:16384
	ds_read_b128 v[190:193], v224 offset:17408
	ds_read_b128 v[194:197], v224 offset:18432
	ds_read_b128 v[198:201], v224 offset:19456
	ds_read_b128 v[226:229], v224 offset:20480
	ds_read_b128 v[230:233], v224 offset:21504
	ds_read_b128 v[234:237], v224 offset:22528
	ds_read_b128 v[238:241], v224 offset:23552
	global_load_lds_dwordx4 v[166:167], off
	s_add_i32 m0, s73, 0x2000
	s_add_u32 s88, s22, 0x160000
	v_lshl_add_u64 v[242:243], s[22:23], 0, v[176:177]
	s_addc_u32 s89, s23, 0
	s_add_i32 s72, s72, s34
	global_load_lds_dwordx4 v[242:243], off
	v_lshl_add_u64 v[244:245], s[88:89], 0, v[168:169]
	s_mov_b32 m0, s72
	v_lshl_add_u64 v[246:247], s[24:25], 0, v[176:177]
	global_load_lds_dwordx4 v[244:245], off
	v_lshl_add_u64 v[244:245], s[88:89], 0, v[176:177]
	s_add_i32 m0, s72, 0x2000
	s_nop 0
	global_load_lds_dwordx4 v[244:245], off
	v_lshl_add_u64 v[244:245], s[24:25], 0, v[168:169]
	s_mov_b32 m0, s35
	s_nop 0
	global_load_lds_dwordx4 v[244:245], off
	s_mov_b32 m0, s36
	s_nop 0
	global_load_lds_dwordx4 v[246:247], off
	s_waitcnt vmcnt(8)
	s_waitcnt lgkmcnt(0)
	s_barrier
; #define PG8_STAGE(bufoff, gbase, voff) do { _Pragma("unroll") for (int _i = 0; _i < 2; ++_i) \
;         __builtin_amdgcn_global_load_lds((const unsigned*)((const char*)(gbase) + (voff)[_i]), (LAS unsigned*)(lds + (bufoff) + ldsw + _i * 8192), 16, 0, 0); } while (0)
; #define PG8_LDA(dst, b, h) do { _Pragma("unroll") for (int m = 0; m < 4; ++m) _Pragma("unroll") for (int k = 0; k < 2; ++k) dst[m][k] = *(const LAS bf16x8*)(lds + PG8_SA(b, h) + aoff + m * 2048 + k * 1024); } while (0)
; #define PG8_LDB(dst, b, h) do { _Pragma("unroll") for (int n = 0; n < 2; ++n) _Pragma("unroll") for (int k = 0; k < 2; ++k) dst[n][k] = *(const LAS bf16x8*)(lds + PG8_SB(b, h) + boff + n * 2048 + k * 1024); } while (0)
; #define PG8_MMA(ai, bj, At, Bt) do { __builtin_amdgcn_s_setprio(1); _Pragma("unroll") for (int m = 0; m < 4; ++m) _Pragma("unroll") for (int n = 0; n < 2; ++n) _Pragma("unroll") for (int k = 0; k < 2; ++k) \
;         acc[ai][bj][m][n] = __builtin_amdgcn_mfma_f32_16x16x32_bf16(Bt[n][k], At[m][k], acc[ai][bj][m][n], 0, 0, 0); __builtin_amdgcn_s_setprio(0); } while (0)
; #define PG8_WAIT_V(n) asm volatile("s_waitcnt vmcnt(" #n ")" ::: "memory")
; #define PG8_WAIT_L(n) asm volatile("s_waitcnt lgkmcnt(" #n ")" ::: "memory")
; #define PG8_BAR __builtin_amdgcn_s_barrier()
; #define PG8_SCHED __builtin_amdgcn_sched_barrier(0)
; template <class Epi>
; __device__ __forceinline__ void gemm_phase(LAS unsigned char* lds, const Sched& S, const Epi& E) {
;     ...
;             PG8_WAIT_V(8); PG8_WAIT_L(0); PG8_BAR; PG8_MMA(1, 0, At, B0); PG8_MMA(1, 1, At, B1); PG8_BAR; PG8_SCHED;
;             PG8_LDB(B0, 1, 0); PG8_LDB(B1, 1, 1); PG8_SCHED; PG8_LDA(At, 1, 0); PG8_STAGE(PG8_SA(0, 1), a2 + hstepA, voffA);
;             PG8_WAIT_V(8); PG8_WAIT_L(0); PG8_BAR; PG8_MMA(0, 0, At, B0); PG8_MMA(0, 1, At, B1); PG8_BAR; PG8_SCHED;
	s_setprio 1
	s_waitcnt lgkmcnt(0)
	v_mfma_f32_16x16x32_bf16 v[62:65], v[130:133], v[162:165], v[62:65]
	v_mfma_f32_16x16x32_bf16 v[58:61], v[138:141], v[162:165], v[58:61]
	v_mfma_f32_16x16x32_bf16 v[54:57], v[130:133], v[194:197], v[54:57]
	v_mfma_f32_16x16x32_bf16 v[42:45], v[138:141], v[194:197], v[42:45]
	v_mfma_f32_16x16x32_bf16 v[30:33], v[130:133], v[226:229], v[30:33]
	v_mfma_f32_16x16x32_bf16 v[26:29], v[138:141], v[226:229], v[26:29]
	v_mfma_f32_16x16x32_bf16 v[22:25], v[130:133], v[234:237], v[22:25]
	v_mfma_f32_16x16x32_bf16 v[10:13], v[138:141], v[234:237], v[10:13]
	v_mfma_f32_16x16x32_bf16 v[62:65], v[134:137], v[190:193], v[62:65]
	v_mfma_f32_16x16x32_bf16 v[58:61], v[142:145], v[190:193], v[58:61]
	v_mfma_f32_16x16x32_bf16 v[54:57], v[134:137], v[198:201], v[54:57]
	v_mfma_f32_16x16x32_bf16 v[42:45], v[142:145], v[198:201], v[42:45]
	v_mfma_f32_16x16x32_bf16 v[30:33], v[134:137], v[230:233], v[30:33]
	v_mfma_f32_16x16x32_bf16 v[26:29], v[142:145], v[230:233], v[26:29]
	v_mfma_f32_16x16x32_bf16 v[22:25], v[134:137], v[238:241], v[22:25]
	v_mfma_f32_16x16x32_bf16 v[10:13], v[142:145], v[238:241], v[10:13]
	s_setprio 0
	s_setprio 1
	v_mfma_f32_16x16x32_bf16 v[50:53], v[146:149], v[162:165], v[50:53]
	v_mfma_f32_16x16x32_bf16 v[46:49], v[154:157], v[162:165], v[46:49]
	v_mfma_f32_16x16x32_bf16 v[38:41], v[146:149], v[194:197], v[38:41]
	v_mfma_f32_16x16x32_bf16 v[34:37], v[154:157], v[194:197], v[34:37]
	v_mfma_f32_16x16x32_bf16 v[18:21], v[146:149], v[226:229], v[18:21]
	v_mfma_f32_16x16x32_bf16 v[14:17], v[154:157], v[226:229], v[14:17]
	v_mfma_f32_16x16x32_bf16 v[6:9], v[146:149], v[234:237], v[6:9]
	v_mfma_f32_16x16x32_bf16 v[2:5], v[154:157], v[234:237], v[2:5]
	v_mfma_f32_16x16x32_bf16 v[50:53], v[150:153], v[190:193], v[50:53]
	v_mfma_f32_16x16x32_bf16 v[46:49], v[158:161], v[190:193], v[46:49]
	v_mfma_f32_16x16x32_bf16 v[38:41], v[150:153], v[198:201], v[38:41]
	v_mfma_f32_16x16x32_bf16 v[34:37], v[158:161], v[198:201], v[34:37]
	s_setprio 2
	s_barrier
	v_mfma_f32_16x16x32_bf16 v[18:21], v[150:153], v[230:233], v[18:21]
	v_mfma_f32_16x16x32_bf16 v[14:17], v[158:161], v[230:233], v[14:17]
	v_mfma_f32_16x16x32_bf16 v[6:9], v[150:153], v[238:241], v[6:9]
	v_mfma_f32_16x16x32_bf16 v[2:5], v[158:161], v[238:241], v[2:5]
	s_setprio 0
	s_add_i32 s72, 0, 0x18000
	s_add_i32 s73, 0, 0x1c000
	v_add_u32_e32 v142, s72, v222
	v_add_u32_e32 v158, s73, v222
	ds_read_b128 v[130:133], v142
	ds_read_b128 v[134:137], v142 offset:1024
	ds_read_b128 v[138:141], v142 offset:2048
	ds_read_b128 v[142:145], v142 offset:3072
	ds_read_b128 v[146:149], v158
	ds_read_b128 v[150:153], v158 offset:1024
	ds_read_b128 v[154:157], v158 offset:2048
	ds_read_b128 v[158:161], v158 offset:3072
	s_add_u32 s24, s24, 0x160000
	s_addc_u32 s25, s25, 0
	s_mov_b32 m0, s37
	v_lshl_add_u64 v[248:249], s[24:25], 0, v[168:169]
	ds_read_b128 v[162:165], v224 offset:32768
	ds_read_b128 v[190:193], v224 offset:33792
	ds_read_b128 v[194:197], v224 offset:34816
	ds_read_b128 v[198:201], v224 offset:35840
	ds_read_b128 v[226:229], v224 offset:36864
	ds_read_b128 v[230:233], v224 offset:37888
	ds_read_b128 v[234:237], v224 offset:38912
	ds_read_b128 v[238:241], v224 offset:39936
	global_load_lds_dwordx4 v[248:249], off
	v_lshl_add_u64 v[248:249], s[24:25], 0, v[176:177]
	s_mov_b32 m0, s38
	s_nop 0
	global_load_lds_dwordx4 v[248:249], off
	s_waitcnt vmcnt(8)
	s_waitcnt lgkmcnt(0)
	s_barrier
	s_setprio 1
	s_waitcnt lgkmcnt(0)
	v_mfma_f32_16x16x32_bf16 v[126:129], v[130:133], v[162:165], v[126:129]
	v_mfma_f32_16x16x32_bf16 v[122:125], v[138:141], v[162:165], v[122:125]
	v_mfma_f32_16x16x32_bf16 v[118:121], v[130:133], v[194:197], v[118:121]
	v_mfma_f32_16x16x32_bf16 v[106:109], v[138:141], v[194:197], v[106:109]
	v_mfma_f32_16x16x32_bf16 v[94:97], v[130:133], v[226:229], v[94:97]
	v_mfma_f32_16x16x32_bf16 v[90:93], v[138:141], v[226:229], v[90:93]
	v_mfma_f32_16x16x32_bf16 v[86:89], v[130:133], v[234:237], v[86:89]
	v_mfma_f32_16x16x32_bf16 v[74:77], v[138:141], v[234:237], v[74:77]
	v_mfma_f32_16x16x32_bf16 v[126:129], v[134:137], v[190:193], v[126:129]
	v_mfma_f32_16x16x32_bf16 v[122:125], v[142:145], v[190:193], v[122:125]
	v_mfma_f32_16x16x32_bf16 v[118:121], v[134:137], v[198:201], v[118:121]
	v_mfma_f32_16x16x32_bf16 v[106:109], v[142:145], v[198:201], v[106:109]
	v_mfma_f32_16x16x32_bf16 v[94:97], v[134:137], v[230:233], v[94:97]
	v_mfma_f32_16x16x32_bf16 v[90:93], v[142:145], v[230:233], v[90:93]
	v_mfma_f32_16x16x32_bf16 v[86:89], v[134:137], v[238:241], v[86:89]
	v_mfma_f32_16x16x32_bf16 v[74:77], v[142:145], v[238:241], v[74:77]
	s_setprio 0
	s_setprio 1
	v_mfma_f32_16x16x32_bf16 v[114:117], v[146:149], v[162:165], v[114:117]
	v_mfma_f32_16x16x32_bf16 v[110:113], v[154:157], v[162:165], v[110:113]
	v_mfma_f32_16x16x32_bf16 v[102:105], v[146:149], v[194:197], v[102:105]
	v_mfma_f32_16x16x32_bf16 v[98:101], v[154:157], v[194:197], v[98:101]
	v_mfma_f32_16x16x32_bf16 v[82:85], v[146:149], v[226:229], v[82:85]
	v_mfma_f32_16x16x32_bf16 v[78:81], v[154:157], v[226:229], v[78:81]
	v_mfma_f32_16x16x32_bf16 v[70:73], v[146:149], v[234:237], v[70:73]
	v_mfma_f32_16x16x32_bf16 v[66:69], v[154:157], v[234:237], v[66:69]
	v_mfma_f32_16x16x32_bf16 v[114:117], v[150:153], v[190:193], v[114:117]
	v_mfma_f32_16x16x32_bf16 v[110:113], v[158:161], v[190:193], v[110:113]
	v_mfma_f32_16x16x32_bf16 v[102:105], v[150:153], v[198:201], v[102:105]
	v_mfma_f32_16x16x32_bf16 v[98:101], v[158:161], v[198:201], v[98:101]
	s_setprio 2
	s_barrier
; #define PG8_STAGE(bufoff, gbase, voff) do { _Pragma("unroll") for (int _i = 0; _i < 2; ++_i) \
;         __builtin_amdgcn_global_load_lds((const unsigned*)((const char*)(gbase) + (voff)[_i]), (LAS unsigned*)(lds + (bufoff) + ldsw + _i * 8192), 16, 0, 0); } while (0)
; #define PG8_LDA(dst, b, h) do { _Pragma("unroll") for (int m = 0; m < 4; ++m) _Pragma("unroll") for (int k = 0; k < 2; ++k) dst[m][k] = *(const LAS bf16x8*)(lds + PG8_SA(b, h) + aoff + m * 2048 + k * 1024); } while (0)
; #define PG8_MMA(ai, bj, At, Bt) do { __builtin_amdgcn_s_setprio(1); _Pragma("unroll") for (int m = 0; m < 4; ++m) _Pragma("unroll") for (int n = 0; n < 2; ++n) _Pragma("unroll") for (int k = 0; k < 2; ++k) \
;         acc[ai][bj][m][n] = __builtin_amdgcn_mfma_f32_16x16x32_bf16(Bt[n][k], At[m][k], acc[ai][bj][m][n], 0, 0, 0); __builtin_amdgcn_s_setprio(0); } while (0)
; #define PG8_WAIT_V(n) asm volatile("s_waitcnt vmcnt(" #n ")" ::: "memory")
; #define PG8_WAIT_L(n) asm volatile("s_waitcnt lgkmcnt(" #n ")" ::: "memory")
; #define PG8_BAR __builtin_amdgcn_s_barrier()
; #define PG8_SCHED __builtin_amdgcn_sched_barrier(0)
; template <class Epi>
; __device__ __forceinline__ void gemm_phase(LAS unsigned char* lds, const Sched& S, const Epi& E) {
;     ...
;             PG8_WAIT_V(8); PG8_WAIT_L(0); PG8_BAR; PG8_MMA(0, 0, At, B0); PG8_MMA(0, 1, At, B1); PG8_BAR; PG8_SCHED;
;             PG8_LDA(At, 1, 1); PG8_STAGE(PG8_SB(1, 0), b3, voffB); PG8_STAGE(PG8_SB(1, 1), b3 + hstepB, voffB); PG8_STAGE(PG8_SA(1, 0), a3, voffA);
;             PG8_WAIT_V(8); PG8_WAIT_L(0); PG8_BAR; PG8_MMA(1, 0, At, B0); PG8_MMA(1, 1, At, B1); PG8_BAR; PG8_SCHED;
;         }
;         if (wr == 0) PG8_BAR;
	v_mfma_f32_16x16x32_bf16 v[82:85], v[150:153], v[230:233], v[82:85]
	v_mfma_f32_16x16x32_bf16 v[78:81], v[158:161], v[230:233], v[78:81]
	v_mfma_f32_16x16x32_bf16 v[70:73], v[150:153], v[238:241], v[70:73]
	v_mfma_f32_16x16x32_bf16 v[66:69], v[158:161], v[238:241], v[66:69]
	s_setprio 0
	s_add_i32 s24, s72, s34
	v_lshl_add_u64 v[166:167], v[166:167], 0, s[0:1]
	s_mov_b32 m0, s24
	ds_read_b128 v[162:165], v224 offset:49152
	ds_read_b128 v[190:193], v224 offset:50176
	ds_read_b128 v[194:197], v224 offset:51200
	ds_read_b128 v[198:201], v224 offset:52224
	ds_read_b128 v[226:229], v224 offset:53248
	ds_read_b128 v[230:233], v224 offset:54272
	ds_read_b128 v[234:237], v224 offset:55296
	ds_read_b128 v[238:241], v224 offset:56320
	global_load_lds_dwordx4 v[166:167], off
	s_add_i32 m0, s24, 0x2000
	s_add_u32 s22, s22, 0x160080
	v_lshl_add_u64 v[166:167], v[242:243], 0, s[0:1]
	s_addc_u32 s23, s23, 0
	s_add_i32 s24, s73, s34
	global_load_lds_dwordx4 v[166:167], off
	v_lshl_add_u64 v[166:167], s[22:23], 0, v[168:169]
	s_mov_b32 m0, s24
	s_nop 0
	global_load_lds_dwordx4 v[166:167], off
	v_lshl_add_u64 v[166:167], s[22:23], 0, v[176:177]
	s_add_i32 m0, s24, 0x2000
	s_nop 0
	global_load_lds_dwordx4 v[166:167], off
	v_lshl_add_u64 v[166:167], v[244:245], 0, s[0:1]
	s_mov_b32 m0, s39
	s_nop 0
	global_load_lds_dwordx4 v[166:167], off
	v_lshl_add_u64 v[166:167], v[246:247], 0, s[0:1]
	s_mov_b32 m0, s58
	s_nop 0
	global_load_lds_dwordx4 v[166:167], off
	s_waitcnt vmcnt(8)
	s_waitcnt lgkmcnt(0)
	s_barrier
	s_setprio 1
	s_waitcnt lgkmcnt(0)
	v_mfma_f32_16x16x32_bf16 v[62:65], v[130:133], v[162:165], v[62:65]
	v_mfma_f32_16x16x32_bf16 v[58:61], v[138:141], v[162:165], v[58:61]
	v_mfma_f32_16x16x32_bf16 v[54:57], v[130:133], v[194:197], v[54:57]
	v_mfma_f32_16x16x32_bf16 v[42:45], v[138:141], v[194:197], v[42:45]
	v_mfma_f32_16x16x32_bf16 v[30:33], v[130:133], v[226:229], v[30:33]
	v_mfma_f32_16x16x32_bf16 v[26:29], v[138:141], v[226:229], v[26:29]
	v_mfma_f32_16x16x32_bf16 v[22:25], v[130:133], v[234:237], v[22:25]
	v_mfma_f32_16x16x32_bf16 v[10:13], v[138:141], v[234:237], v[10:13]
	v_mfma_f32_16x16x32_bf16 v[62:65], v[134:137], v[190:193], v[62:65]
	v_mfma_f32_16x16x32_bf16 v[58:61], v[142:145], v[190:193], v[58:61]
	v_mfma_f32_16x16x32_bf16 v[54:57], v[134:137], v[198:201], v[54:57]
	v_mfma_f32_16x16x32_bf16 v[42:45], v[142:145], v[198:201], v[42:45]
	v_mfma_f32_16x16x32_bf16 v[30:33], v[134:137], v[230:233], v[30:33]
	v_mfma_f32_16x16x32_bf16 v[26:29], v[142:145], v[230:233], v[26:29]
	v_mfma_f32_16x16x32_bf16 v[22:25], v[134:137], v[238:241], v[22:25]
	v_mfma_f32_16x16x32_bf16 v[10:13], v[142:145], v[238:241], v[10:13]
	s_setprio 0
	s_setprio 1
	v_mfma_f32_16x16x32_bf16 v[50:53], v[146:149], v[162:165], v[50:53]
	v_mfma_f32_16x16x32_bf16 v[46:49], v[154:157], v[162:165], v[46:49]
	v_mfma_f32_16x16x32_bf16 v[38:41], v[146:149], v[194:197], v[38:41]
	v_mfma_f32_16x16x32_bf16 v[34:37], v[154:157], v[194:197], v[34:37]
	v_mfma_f32_16x16x32_bf16 v[18:21], v[146:149], v[226:229], v[18:21]
	v_mfma_f32_16x16x32_bf16 v[14:17], v[154:157], v[226:229], v[14:17]
	v_mfma_f32_16x16x32_bf16 v[6:9], v[146:149], v[234:237], v[6:9]
	v_mfma_f32_16x16x32_bf16 v[2:5], v[154:157], v[234:237], v[2:5]
	v_mfma_f32_16x16x32_bf16 v[50:53], v[150:153], v[190:193], v[50:53]
	v_mfma_f32_16x16x32_bf16 v[46:49], v[158:161], v[190:193], v[46:49]
	v_mfma_f32_16x16x32_bf16 v[38:41], v[150:153], v[198:201], v[38:41]
	v_mfma_f32_16x16x32_bf16 v[34:37], v[158:161], v[198:201], v[34:37]
	s_setprio 2
	s_barrier
	v_mfma_f32_16x16x32_bf16 v[18:21], v[150:153], v[230:233], v[18:21]
	v_mfma_f32_16x16x32_bf16 v[14:17], v[158:161], v[230:233], v[14:17]
	v_mfma_f32_16x16x32_bf16 v[6:9], v[150:153], v[238:241], v[6:9]
	v_mfma_f32_16x16x32_bf16 v[2:5], v[158:161], v[238:241], v[2:5]
	s_setprio 0
	s_add_u32 s4, s4, 0x100
	s_addc_u32 s5, s5, 0
	s_add_u32 vcc_lo, vcc_lo, 0x100
	s_addc_u32 vcc_hi, vcc_hi, 0
	s_cmp_ge_i32 s49, s94
	s_mov_b32 s22, s49
	s_cbranch_scc0 .LBB0_2391
	s_and_b64 vcc, exec, s[10:11]
	s_cbranch_vccz .LBB0_2394
	s_barrier
